# s_setprio 1/0 around the MFMA clusters of the attention (mixer) loops, as the GEMM loops already have
# baseline (speedup 1.0000x reference)
.LBB0_1011:
	s_or_b64 exec, exec, s[2:3]
	v_lshlrev_b32_e32 v112, 13, v166
	v_lshl_add_u64 v[64:65], v[140:141], 0, v[112:113]
	v_add_co_u32_e32 v64, vcc, 0xffffe000, v64
	ds_write_b128 v115, v[132:135] offset:26624
	s_nop 0
	v_addc_co_u32_e32 v65, vcc, -1, v65, vcc
	global_load_dwordx4 v[124:127], v[64:65], off
	ds_read_b128 v[132:135], v180 offset:6656
	ds_read_b128 v[128:131], v180
	ds_read_b128 v[136:139], v180 offset:32
	s_waitcnt lgkmcnt(0)
	s_setprio 1
	v_mfma_f32_32x32x16_bf16 v[64:79], v[128:131], v[100:103], v[32:47]
	s_setprio 0
	ds_read_b128 v[140:143], v180 offset:6688
	v_exp_f32_e32 v172, v80
	v_exp_f32_e32 v173, v81
	v_exp_f32_e32 v174, v82
	v_exp_f32_e32 v175, v83
	v_exp_f32_e32 v164, v88
	v_exp_f32_e32 v165, v89
	s_setprio 1
	v_mfma_f32_32x32x16_bf16 v[64:79], v[136:139], v[104:107], v[64:79]
	s_setprio 0
	ds_read_b128 v[128:131], v180 offset:64
	ds_read_b128 v[136:139], v180 offset:6720
	v_exp_f32_e32 v166, v90
	v_exp_f32_e32 v167, v91
	v_exp_f32_e32 v168, v92
	v_exp_f32_e32 v169, v93
	v_exp_f32_e32 v170, v94
	v_exp_f32_e32 v171, v95
	s_waitcnt lgkmcnt(0)
	s_setprio 1
	v_mfma_f32_32x32x16_bf16 v[64:79], v[128:131], v[108:111], v[64:79]
	s_setprio 0
	ds_read_b128 v[128:131], v180 offset:96
	ds_read_b128 v[146:149], v180 offset:6752
	v_exp_f32_e32 v162, v48
	v_exp_f32_e32 v163, v49
	v_exp_f32_e32 v50, v50
	v_exp_f32_e32 v51, v51
	v_exp_f32_e32 v52, v52
	v_exp_f32_e32 v53, v53
	s_waitcnt lgkmcnt(0)
	s_setprio 1
	v_mfma_f32_32x32x16_bf16 v[64:79], v[128:131], v[116:119], v[64:79]
	s_setprio 0
	ds_read_b128 v[128:131], v180 offset:128
	ds_read_b128 v[150:153], v180 offset:6784
	v_exp_f32_e32 v54, v54
	v_exp_f32_e32 v55, v55
	v_exp_f32_e32 v48, v56
	v_exp_f32_e32 v49, v57
	v_exp_f32_e32 v56, v58
	v_exp_f32_e32 v57, v59
	s_waitcnt lgkmcnt(0)
	s_setprio 1
	v_mfma_f32_32x32x16_bf16 v[64:79], v[128:131], v[120:123], v[64:79]
	s_setprio 0
	ds_read_b128 v[154:157], v180 offset:160
	ds_read_b128 v[128:131], v180 offset:6816
	v_exp_f32_e32 v58, v60
	v_exp_f32_e32 v59, v61
	v_exp_f32_e32 v60, v62
	v_exp_f32_e32 v61, v63
	v_pk_add_f32 v[62:63], v[166:167], v[56:57]
	v_lshlrev_b32_e32 v112, 1, v177
	s_waitcnt lgkmcnt(0)
	s_setprio 1
	v_mfma_f32_32x32x16_bf16 v[64:79], v[154:157], v[96:99], v[64:79]
	s_setprio 0
	v_exp_f32_e32 v154, v84
	v_exp_f32_e32 v155, v85
	v_exp_f32_e32 v156, v86
	v_exp_f32_e32 v157, v87
	s_setprio 1
	v_mfma_f32_32x32x16_bf16 v[80:95], v[132:135], v[100:103], v[32:47]
	s_setprio 0
	v_add_f32_e64 v134, v168, v58
	v_add_f32_e64 v135, v169, v59
	v_add_f32_e64 v132, v170, v60
	v_add_f32_e64 v133, v171, v61
	s_nop 2
	v_exp_f32_e32 v181, v73
	v_exp_f32_e32 v182, v74
	v_exp_f32_e32 v183, v75
	v_exp_f32_e32 v184, v76
	v_exp_f32_e32 v185, v77
	s_setprio 1
	v_mfma_f32_32x32x16_bf16 v[80:95], v[140:143], v[104:107], v[80:95]
	s_setprio 0
	v_add_f32_e64 v142, v154, v52
	v_add_f32_e64 v143, v155, v53
	v_add_f32_e64 v140, v164, v48
	v_add_f32_e64 v141, v165, v49
	v_cvt_pk_bf16_f32 v48, v48, v49
	v_cvt_pk_bf16_f32 v49, v56, v57
	v_exp_f32_e32 v186, v78
	v_exp_f32_e32 v187, v79
	v_add_f32_e32 v140, v140, v141
	s_setprio 1
	v_mfma_f32_32x32x16_bf16 v[80:95], v[136:139], v[108:111], v[80:95]
	s_setprio 0
	v_add_f32_e64 v136, v174, v50
	v_add_f32_e64 v137, v175, v51
	v_add_f32_e64 v138, v156, v54
	v_add_f32_e64 v139, v157, v55
	s_setprio 1
	v_mfma_f32_32x32x16_bf16 v[80:95], v[146:149], v[116:119], v[80:95]
	s_setprio 0
	v_add_f32_e64 v146, v172, v162
	v_add_f32_e64 v147, v173, v163
	v_pk_mov_b32 v[148:149], v[146:147], v[136:137] op_sel:[1,0]
	v_mov_b32_e32 v147, v137
	v_pk_add_f32 v[136:137], v[148:149], v[146:147]
	v_cvt_pk_bf16_f32 v148, v154, v155
	v_cvt_pk_bf16_f32 v149, v156, v157
	s_setprio 1
	v_mfma_f32_32x32x16_bf16 v[80:95], v[150:153], v[120:123], v[80:95]
	s_setprio 0
	ds_read_b64_tr_b16 v[150:151], v179 offset:35840
	ds_read_b64_tr_b16 v[152:153], v179 offset:36992
	ds_read_b64_tr_b16 v[154:155], v179 offset:35904
	ds_read_b64_tr_b16 v[156:157], v179 offset:37056
	v_pk_mov_b32 v[146:147], v[142:143], v[138:139] op_sel:[1,0]
	v_mov_b32_e32 v143, v139
	v_pk_add_f32 v[138:139], v[146:147], v[142:143]
	v_cvt_pk_bf16_f32 v146, v172, v173
	v_cvt_pk_bf16_f32 v147, v174, v175
	v_add_f32_e32 v142, v62, v63
	s_setprio 1
	v_mfma_f32_32x32x16_bf16 v[80:95], v[128:131], v[96:99], v[80:95]
	s_setprio 0
	v_exp_f32_e32 v172, v70
	v_exp_f32_e32 v173, v71
	v_pk_add_f32 v[136:137], v[136:137], v[136:137] op_sel:[0,1] op_sel_hi:[1,0]
	v_pk_add_f32 v[138:139], v[138:139], v[138:139] op_sel:[0,1] op_sel_hi:[1,0]
	s_waitcnt lgkmcnt(0)
	s_setprio 1
	v_mfma_f32_32x32x16_bf16 v[0:15], v[150:153], v[146:149], v[0:15]
	s_setprio 0
	s_nop 5
	v_exp_f32_e32 v80, v80
	v_exp_f32_e32 v81, v81
	v_exp_f32_e32 v174, v86
	v_exp_f32_e32 v175, v87
	v_exp_f32_e32 v73, v89
	v_exp_f32_e32 v74, v90
	v_exp_f32_e32 v75, v91
	s_setprio 1
	v_mfma_f32_32x32x16_bf16 v[16:31], v[154:157], v[146:149], v[16:31]
	s_setprio 0
	ds_read_b64_tr_b16 v[150:151], v179 offset:38144
	ds_read_b64_tr_b16 v[152:153], v179 offset:39296
	ds_read_b64_tr_b16 v[154:155], v179 offset:38208
	ds_read_b64_tr_b16 v[156:157], v179 offset:39360
	v_cvt_pk_bf16_f32 v146, v164, v165
	v_cvt_pk_bf16_f32 v147, v166, v167
	v_cvt_pk_bf16_f32 v148, v168, v169
	v_cvt_pk_bf16_f32 v149, v170, v171
	v_exp_f32_e32 v168, v68
	v_exp_f32_e32 v170, v84
	s_waitcnt lgkmcnt(0)
	s_setprio 1
	v_mfma_f32_32x32x16_bf16 v[0:15], v[150:153], v[146:149], v[0:15]
	s_setprio 0
	v_exp_f32_e32 v169, v69
	v_exp_f32_e32 v171, v85
	v_exp_f32_e32 v166, v82
	v_exp_f32_e32 v167, v83
	v_pk_add_f32 v[84:85], v[172:173], v[174:175]
	v_exp_f32_e32 v76, v92
	v_exp_f32_e32 v77, v93
	s_setprio 1
	v_mfma_f32_32x32x16_bf16 v[16:31], v[154:157], v[146:149], v[16:31]
	s_setprio 0
	v_cvt_pk_bf16_f32 v147, v50, v51
	v_cvt_pk_bf16_f32 v148, v52, v53
	ds_read_b64_tr_b16 v[50:51], v179 offset:40448
	ds_read_b64_tr_b16 v[52:53], v179 offset:41600
	ds_read_b64_tr_b16 v[150:151], v179 offset:40512
	ds_read_b64_tr_b16 v[152:153], v179 offset:41664
	v_cvt_pk_bf16_f32 v146, v162, v163
	v_cvt_pk_bf16_f32 v149, v54, v55
	v_exp_f32_e32 v78, v94
	v_exp_f32_e32 v79, v95
	s_waitcnt lgkmcnt(0)
	s_setprio 1
	v_mfma_f32_32x32x16_bf16 v[0:15], v[50:53], v[146:149], v[0:15]
	s_setprio 0
	v_cvt_pk_bf16_f32 v50, v58, v59
	ds_read_b64_tr_b16 v[52:53], v179 offset:42752
	ds_read_b64_tr_b16 v[54:55], v179 offset:43904
	ds_read_b64_tr_b16 v[56:57], v179 offset:42816
	ds_read_b64_tr_b16 v[58:59], v179 offset:43968
	s_waitcnt lgkmcnt(0)
	s_barrier
	s_waitcnt vmcnt(0)
	ds_write_b128 v115, v[124:127] offset:35840
	v_cvt_pk_bf16_f32 v51, v60, v61
	s_setprio 1
	v_mfma_f32_32x32x16_bf16 v[16:31], v[150:153], v[146:149], v[16:31]
	s_setprio 0
	ds_read_b128 v[128:131], v180 offset:19968
	ds_read_b128 v[124:127], v180 offset:13312
	ds_read_b128 v[146:149], v180 offset:13344
	ds_read_b128 v[150:153], v180 offset:20000
	v_add_f32_e64 v70, v186, v78
	v_add_f32_e64 v71, v187, v79
	v_pk_add_f32 v[68:69], v[184:185], v[76:77]
	v_add_f32_e32 v70, v70, v71
	v_add_f32_e32 v68, v68, v69
	s_setprio 1
	v_mfma_f32_32x32x16_bf16 v[0:15], v[52:55], v[48:51], v[0:15]
	v_mfma_f32_32x32x16_bf16 v[16:31], v[56:59], v[48:51], v[16:31]
	s_waitcnt lgkmcnt(2)
	v_mfma_f32_32x32x16_bf16 v[48:63], v[124:127], v[100:103], v[32:47]
	s_waitcnt lgkmcnt(1)
	v_mfma_f32_32x32x16_bf16 v[48:63], v[146:149], v[104:107], v[48:63]
	ds_read_b128 v[124:127], v180 offset:13376
	ds_read_b128 v[146:149], v180 offset:20032
	s_waitcnt lgkmcnt(1)
	v_mfma_f32_32x32x16_bf16 v[48:63], v[124:127], v[108:111], v[48:63]
	ds_read_b128 v[124:127], v180 offset:13408
	ds_read_b128 v[154:157], v180 offset:20064
	s_waitcnt lgkmcnt(1)
	v_mfma_f32_32x32x16_bf16 v[48:63], v[124:127], v[116:119], v[48:63]
	ds_read_b128 v[124:127], v180 offset:13440
	ds_read_b128 v[158:161], v180 offset:20096
	v_mfma_f32_32x32x16_bf16 v[32:47], v[128:131], v[100:103], v[32:47]
	s_waitcnt lgkmcnt(1)
	v_mfma_f32_32x32x16_bf16 v[48:63], v[124:127], v[120:123], v[48:63]
	s_setprio 0
	ds_read_b128 v[162:165], v180 offset:13472
	ds_read_b128 v[124:127], v180 offset:20128
	v_exp_f32_e32 v180, v72
	v_exp_f32_e32 v72, v88
	v_pk_add_f32 v[88:89], v[168:169], v[170:171]
	v_pk_add_f32 v[82:83], v[180:181], v[72:73]
	s_setprio 1
	v_mfma_f32_32x32x16_bf16 v[32:47], v[150:153], v[104:107], v[32:47]
	s_setprio 0
	v_mov_b32_e32 v91, v88
	v_cvt_pk_bf16_f32 v72, v72, v73
	v_cvt_pk_bf16_f32 v73, v74, v75
	s_waitcnt lgkmcnt(1)
	s_setprio 1
	v_mfma_f32_32x32x16_bf16 v[48:63], v[162:165], v[96:99], v[48:63]
	s_setprio 0
	v_exp_f32_e32 v162, v64
	v_exp_f32_e32 v163, v65
	v_exp_f32_e32 v164, v66
	v_exp_f32_e32 v165, v67
	v_pk_add_f32 v[66:67], v[182:183], v[74:75]
	v_pk_add_f32 v[86:87], v[162:163], v[80:81]
	v_cvt_pk_bf16_f32 v80, v80, v81
	s_setprio 1
	v_mfma_f32_32x32x16_bf16 v[32:47], v[146:149], v[108:111], v[32:47]
	s_setprio 0
	v_add_f32_e64 v64, v164, v166
	v_add_f32_e64 v65, v165, v167
	v_mov_b32_e32 v90, v86
	v_mov_b32_e32 v88, v87
	v_add_f32_e64 v86, v90, v88
	v_add_f32_e64 v87, v91, v89
	v_mov_b32_e32 v88, v64
	v_mov_b32_e32 v89, v84
	v_mov_b32_e32 v84, v65
	v_pk_add_f32 v[64:65], v[88:89], v[84:85]
	v_pk_mov_b32 v[84:85], v[82:83], v[66:67] op_sel:[1,0]
	v_pk_add_f32 v[64:65], v[86:87], v[64:65]
	ds_read_b64_tr_b16 v[86:87], v179 offset:26624
	ds_read_b64_tr_b16 v[88:89], v179 offset:27776
	ds_read_b64_tr_b16 v[90:91], v179 offset:26688
	ds_read_b64_tr_b16 v[92:93], v179 offset:27840
	v_mov_b32_e32 v83, v67
	v_pk_add_f32 v[66:67], v[84:85], v[82:83]
	v_cvt_pk_bf16_f32 v82, v162, v163
	v_cvt_pk_bf16_f32 v83, v164, v165
	v_cvt_pk_bf16_f32 v84, v168, v169
	v_cvt_pk_bf16_f32 v85, v172, v173
	s_setprio 1
	v_mfma_f32_32x32x16_bf16 v[32:47], v[154:157], v[116:119], v[32:47]
	s_setprio 0
	v_cvt_pk_bf16_f32 v81, v166, v167
	v_cvt_pk_bf16_f32 v74, v76, v77
	v_cvt_pk_bf16_f32 v75, v78, v79
	v_exp_f32_e32 v56, v56
	v_exp_f32_e32 v57, v57
	v_exp_f32_e32 v58, v58
	v_exp_f32_e32 v59, v59
	s_waitcnt lgkmcnt(2)
	s_setprio 1
	v_mfma_f32_32x32x16_bf16 v[0:15], v[86:89], v[82:85], v[0:15]
	v_pk_add_f32 v[64:65], v[64:65], v[64:65] op_sel:[0,1] op_sel_hi:[1,0]
	v_pk_add_f32 v[66:67], v[66:67], v[66:67] op_sel:[0,1] op_sel_hi:[1,0]
	s_waitcnt lgkmcnt(0)
	v_mfma_f32_32x32x16_bf16 v[16:31], v[90:93], v[82:85], v[16:31]
	s_setprio 0
	ds_read_b64_tr_b16 v[86:87], v179 offset:28928
	ds_read_b64_tr_b16 v[88:89], v179 offset:30080
	ds_read_b64_tr_b16 v[90:91], v179 offset:28992
	ds_read_b64_tr_b16 v[92:93], v179 offset:30144
	v_cvt_pk_bf16_f32 v82, v180, v181
	v_cvt_pk_bf16_f32 v83, v182, v183
	v_cvt_pk_bf16_f32 v84, v184, v185
	v_cvt_pk_bf16_f32 v85, v186, v187
	s_setprio 1
	v_mfma_f32_32x32x16_bf16 v[32:47], v[158:161], v[120:123], v[32:47]
	s_waitcnt lgkmcnt(2)
	v_mfma_f32_32x32x16_bf16 v[0:15], v[86:89], v[82:85], v[0:15]
	s_waitcnt lgkmcnt(0)
	v_mfma_f32_32x32x16_bf16 v[16:31], v[90:93], v[82:85], v[16:31]
	s_setprio 0
	ds_read_b64_tr_b16 v[84:85], v179 offset:31232
	ds_read_b64_tr_b16 v[86:87], v179 offset:32384
	ds_read_b64_tr_b16 v[88:89], v179 offset:31296
	ds_read_b64_tr_b16 v[90:91], v179 offset:32448
	v_cvt_pk_bf16_f32 v82, v170, v171
	v_cvt_pk_bf16_f32 v83, v174, v175
	s_waitcnt lgkmcnt(2)
	s_nop 0
	s_setprio 1
	v_mfma_f32_32x32x16_bf16 v[0:15], v[84:87], v[80:83], v[0:15]
	s_waitcnt lgkmcnt(0)
	v_mfma_f32_32x32x16_bf16 v[16:31], v[88:91], v[80:83], v[16:31]
	s_setprio 0
	ds_read_b64_tr_b16 v[76:77], v179 offset:33536
	ds_read_b64_tr_b16 v[78:79], v179 offset:34688
	ds_read_b64_tr_b16 v[80:81], v179 offset:33600
	ds_read_b64_tr_b16 v[82:83], v179 offset:34752
	s_waitcnt lgkmcnt(0)
	s_barrier
	s_setprio 1
	v_mfma_f32_32x32x16_bf16 v[32:47], v[124:127], v[96:99], v[32:47]
	v_mfma_f32_32x32x16_bf16 v[0:15], v[76:79], v[72:75], v[0:15]
	s_setprio 0
	v_exp_f32_e32 v76, v52
	s_nop 9
	v_exp_f32_e32 v52, v36
	v_exp_f32_e32 v77, v53
	v_exp_f32_e32 v53, v37
	v_exp_f32_e32 v78, v54
	v_exp_f32_e32 v54, v38
	v_exp_f32_e32 v79, v55
	s_setprio 1
	v_mfma_f32_32x32x16_bf16 v[16:31], v[80:83], v[72:75], v[16:31]
	s_setprio 0
	v_exp_f32_e32 v72, v48
	v_exp_f32_e32 v48, v32
	v_exp_f32_e32 v73, v49
	v_exp_f32_e32 v49, v33
	v_exp_f32_e32 v74, v50
	v_exp_f32_e32 v50, v34
	v_exp_f32_e32 v75, v51
	v_exp_f32_e32 v51, v35
	v_exp_f32_e32 v32, v40
	v_exp_f32_e32 v33, v41
	v_exp_f32_e32 v34, v42
	v_exp_f32_e32 v35, v43
	v_exp_f32_e32 v55, v39
	v_exp_f32_e32 v82, v62
	v_exp_f32_e32 v38, v46
	v_exp_f32_e32 v83, v63
	v_exp_f32_e32 v39, v47
	v_pk_add_f32 v[84:85], v[58:59], v[34:35]
	v_pk_add_f32 v[86:87], v[56:57], v[32:33]
	v_pk_add_f32 v[62:63], v[72:73], v[48:49]
	v_pk_mov_b32 v[88:89], v[86:87], v[84:85] op_sel:[1,0]
	v_mov_b32_e32 v87, v85
	v_exp_f32_e32 v80, v60
	v_exp_f32_e32 v36, v44
	v_exp_f32_e32 v81, v61
	v_exp_f32_e32 v37, v45
	v_pk_add_f32 v[44:45], v[78:79], v[54:55]
	v_pk_add_f32 v[46:47], v[76:77], v[52:53]
	v_pk_add_f32 v[60:61], v[74:75], v[50:51]
	v_pk_add_f32 v[84:85], v[88:89], v[86:87]
	v_mov_b32_e32 v86, v134
	v_mov_b32_e32 v87, v62
	v_mov_b32_e32 v62, v135
	v_pk_add_f32 v[62:63], v[86:87], v[62:63]
	v_mov_b32_e32 v86, v132
	v_mov_b32_e32 v87, v60
	v_mov_b32_e32 v60, v133
	v_mov_b32_e32 v141, v46
	v_mov_b32_e32 v143, v47
	v_mov_b32_e32 v137, v44
	v_mov_b32_e32 v139, v45
	v_pk_add_f32 v[40:41], v[82:83], v[38:39]
	v_pk_add_f32 v[60:61], v[86:87], v[60:61]
	v_pk_add_f32 v[46:47], v[140:141], v[142:143]
	v_pk_add_f32 v[44:45], v[136:137], v[138:139]
	v_pk_add_f32 v[60:61], v[62:63], v[60:61]
	v_pk_add_f32 v[44:45], v[46:47], v[44:45]
	v_mov_b32_e32 v67, v40
	v_mov_b32_e32 v65, v41
	v_pk_add_f32 v[42:43], v[80:81], v[36:37]
	v_pk_add_f32 v[44:45], v[60:61], v[44:45]
	v_pk_add_f32 v[40:41], v[66:67], v[64:65]
	ds_read_b64_tr_b16 v[60:61], v179 offset:35840
	ds_read_b64_tr_b16 v[62:63], v179 offset:36992
	ds_read_b64_tr_b16 v[64:65], v179 offset:35904
	ds_read_b64_tr_b16 v[66:67], v179 offset:37056
	v_pk_add_f32 v[84:85], v[84:85], v[84:85] op_sel_hi:[0,1]
	v_mov_b32_e32 v69, v42
	v_mov_b32_e32 v71, v43
	v_mov_b32_e32 v115, v85
	v_pk_add_f32 v[42:43], v[68:69], v[70:71]
	v_pk_add_f32 v[44:45], v[114:115], v[44:45]
	v_pk_add_f32 v[40:41], v[42:43], v[40:41]
	v_cvt_pk_bf16_f32 v42, v72, v73
	v_pk_add_f32 v[40:41], v[40:41], v[44:45]
	v_cvt_pk_bf16_f32 v43, v74, v75
	v_cvt_pk_bf16_f32 v44, v76, v77
	v_cvt_pk_bf16_f32 v45, v78, v79
	v_cvt_pk_bf16_f32 v32, v32, v33
	v_cvt_pk_bf16_f32 v33, v34, v35
	s_waitcnt lgkmcnt(2)
	s_setprio 1
	v_mfma_f32_32x32x16_bf16 v[0:15], v[60:63], v[42:45], v[0:15]
	v_cvt_pk_bf16_f32 v34, v36, v37
	v_cvt_pk_bf16_f32 v35, v38, v39
	s_waitcnt lgkmcnt(0)
	v_mfma_f32_32x32x16_bf16 v[16:31], v[64:67], v[42:45], v[16:31]
	s_setprio 0
	v_cvt_pk_bf16_f32 v42, v56, v57
	v_cvt_pk_bf16_f32 v43, v58, v59
	ds_read_b64_tr_b16 v[56:57], v179 offset:38144
	ds_read_b64_tr_b16 v[58:59], v179 offset:39296
	ds_read_b64_tr_b16 v[60:61], v179 offset:38208
	ds_read_b64_tr_b16 v[62:63], v179 offset:39360
	v_cvt_pk_bf16_f32 v44, v80, v81
	v_cvt_pk_bf16_f32 v45, v82, v83
	s_waitcnt lgkmcnt(2)
	s_nop 0
	s_setprio 1
	v_mfma_f32_32x32x16_bf16 v[0:15], v[56:59], v[42:45], v[0:15]
	s_waitcnt lgkmcnt(0)
	v_mfma_f32_32x32x16_bf16 v[16:31], v[60:63], v[42:45], v[16:31]
	s_setprio 0
	v_cvt_pk_bf16_f32 v42, v48, v49
	v_cvt_pk_bf16_f32 v43, v50, v51
	v_cvt_pk_bf16_f32 v44, v52, v53
	ds_read_b64_tr_b16 v[46:47], v179 offset:40448
	ds_read_b64_tr_b16 v[48:49], v179 offset:41600
	ds_read_b64_tr_b16 v[50:51], v179 offset:40512
	ds_read_b64_tr_b16 v[52:53], v179 offset:41664
	v_cvt_pk_bf16_f32 v45, v54, v55
	s_waitcnt lgkmcnt(2)
	s_nop 0
	s_setprio 1
	v_mfma_f32_32x32x16_bf16 v[0:15], v[46:49], v[42:45], v[0:15]
	s_waitcnt lgkmcnt(0)
	v_mfma_f32_32x32x16_bf16 v[16:31], v[50:53], v[42:45], v[16:31]
	s_setprio 0
	ds_read_b64_tr_b16 v[36:37], v179 offset:42752
	ds_read_b64_tr_b16 v[38:39], v179 offset:43904
	ds_read_b64_tr_b16 v[42:43], v179 offset:42816
	ds_read_b64_tr_b16 v[44:45], v179 offset:43968
	s_waitcnt lgkmcnt(0)
	s_barrier
	s_setprio 1
	v_mfma_f32_32x32x16_bf16 v[0:15], v[36:39], v[32:35], v[0:15]
	v_mfma_f32_32x32x16_bf16 v[16:31], v[42:45], v[32:35], v[16:31]
	s_setprio 0
	v_lshlrev_b32_e32 v33, 2, v178
	v_add_f32_e32 v32, v40, v41
	v_xor_b32_e32 v33, 0x80, v33
	ds_bpermute_b32 v33, v33, v32
	s_waitcnt lgkmcnt(0)
	v_add_f32_e32 v32, v32, v33
	v_div_scale_f32 v33, s[2:3], v32, v32, 1.0
	v_rcp_f32_e32 v34, v33
	s_nop 0
	v_fma_f32 v35, -v33, v34, 1.0
	v_fmac_f32_e32 v34, v35, v34
	v_div_scale_f32 v35, vcc, 1.0, v32, 1.0
	v_mul_f32_e32 v36, v35, v34
	v_fma_f32 v37, -v33, v36, v35
	v_fmac_f32_e32 v36, v37, v34
	v_fma_f32 v33, -v33, v36, v35
	v_div_fmas_f32 v33, v33, v34, v36
	v_div_fixup_f32 v32, v33, v32, 1.0
	v_pk_mul_f32 v[0:1], v[0:1], v[32:33] op_sel_hi:[1,0]
	v_pk_mul_f32 v[2:3], v[2:3], v[32:33] op_sel_hi:[1,0]
	v_mad_i64_i32 v[34:35], s[2:3], v176, s33, v[144:145]
	v_cvt_pk_bf16_f32 v0, v0, v1
	v_cvt_pk_bf16_f32 v1, v2, v3
	v_pk_mul_f32 v[2:3], v[16:17], v[32:33] op_sel_hi:[1,0]
	v_pk_mul_f32 v[16:17], v[18:19], v[32:33] op_sel_hi:[1,0]
	v_lshl_add_u64 v[48:49], v[34:35], 0, v[112:113]
	v_cvt_pk_bf16_f32 v2, v2, v3
	v_cvt_pk_bf16_f32 v3, v16, v17
	global_store_dwordx2 v[48:49], v[0:1], off
	global_store_dwordx2 v[48:49], v[2:3], off offset:64
	v_pk_mul_f32 v[0:1], v[4:5], v[32:33] op_sel_hi:[1,0]
	v_pk_mul_f32 v[2:3], v[6:7], v[32:33] op_sel_hi:[1,0]
	v_cvt_pk_bf16_f32 v0, v0, v1
	v_cvt_pk_bf16_f32 v1, v2, v3
	v_pk_mul_f32 v[2:3], v[20:21], v[32:33] op_sel_hi:[1,0]
	v_pk_mul_f32 v[4:5], v[22:23], v[32:33] op_sel_hi:[1,0]
	v_cvt_pk_bf16_f32 v2, v2, v3
	v_cvt_pk_bf16_f32 v3, v4, v5
	global_store_dwordx2 v[48:49], v[0:1], off offset:16
	global_store_dwordx2 v[48:49], v[2:3], off offset:80
	v_pk_mul_f32 v[0:1], v[8:9], v[32:33] op_sel_hi:[1,0]
	v_pk_mul_f32 v[2:3], v[10:11], v[32:33] op_sel_hi:[1,0]
	v_cvt_pk_bf16_f32 v0, v0, v1
	v_cvt_pk_bf16_f32 v1, v2, v3
	v_pk_mul_f32 v[2:3], v[24:25], v[32:33] op_sel_hi:[1,0]
	v_pk_mul_f32 v[4:5], v[26:27], v[32:33] op_sel_hi:[1,0]
	v_cvt_pk_bf16_f32 v2, v2, v3
	v_cvt_pk_bf16_f32 v3, v4, v5
	global_store_dwordx2 v[48:49], v[0:1], off offset:32
	global_store_dwordx2 v[48:49], v[2:3], off offset:96
	v_pk_mul_f32 v[0:1], v[12:13], v[32:33] op_sel_hi:[1,0]
	v_pk_mul_f32 v[6:7], v[30:31], v[32:33] op_sel_hi:[1,0]
	v_cvt_pk_bf16_f32 v2, v0, v1
	v_pk_mul_f32 v[0:1], v[14:15], v[32:33] op_sel_hi:[1,0]
	s_nop 0
	v_cvt_pk_bf16_f32 v3, v0, v1
	v_pk_mul_f32 v[0:1], v[28:29], v[32:33] op_sel_hi:[1,0]
	s_nop 0
	v_cvt_pk_bf16_f32 v4, v0, v1

.LBB0_1041:
	s_or_b64 exec, exec, s[8:9]
	v_mov_b32_e32 v14, v113
	v_mov_b32_e32 v15, v113
	v_mov_b32_e32 v0, v113
	v_mov_b32_e32 v1, v113
	v_mov_b32_e32 v2, v113
	v_mov_b32_e32 v3, v113
	v_mov_b32_e32 v4, v113
	v_mov_b32_e32 v5, v113
	v_mov_b32_e32 v6, v113
	v_mov_b32_e32 v7, v113
	v_mov_b32_e32 v8, v113
	v_mov_b32_e32 v9, v113
	v_mov_b32_e32 v10, v113
	v_mov_b32_e32 v11, v113
	v_mov_b32_e32 v12, v113
	v_mov_b32_e32 v13, v113
	v_mov_b64_e32 v[94:95], v[14:15]
	v_mov_b64_e32 v[78:79], v[14:15]
	v_mov_b64_e32 v[92:93], v[12:13]
	v_mov_b64_e32 v[90:91], v[10:11]
	v_mov_b64_e32 v[88:89], v[8:9]
	v_mov_b64_e32 v[86:87], v[6:7]
	v_mov_b64_e32 v[84:85], v[4:5]
	v_mov_b64_e32 v[82:83], v[2:3]
	v_mov_b64_e32 v[80:81], v[0:1]
	v_mov_b64_e32 v[76:77], v[12:13]
	v_mov_b64_e32 v[74:75], v[10:11]
	v_mov_b64_e32 v[72:73], v[8:9]
	v_mov_b64_e32 v[70:71], v[6:7]
	v_mov_b64_e32 v[68:69], v[4:5]
	v_mov_b64_e32 v[66:67], v[2:3]
	v_mov_b64_e32 v[64:65], v[0:1]
	s_and_saveexec_b64 s[6:7], s[2:3]
	s_cbranch_execz .LBB0_1043
	v_mul_u32_u24_e32 v22, 0x90, v16
	v_add3_u32 v28, 0, v22, v18
	ds_read_b128 v[24:27], v28
	s_waitcnt lgkmcnt(0)
	s_setprio 1
	v_mfma_f32_32x32x16_bf16 v[80:95], v[24:27], v[96:99], 0
	ds_read_b128 v[24:27], v28 offset:4608
	s_waitcnt lgkmcnt(0)
	v_mfma_f32_32x32x16_bf16 v[64:79], v[24:27], v[96:99], 0
	ds_read_b128 v[24:27], v28 offset:32
	s_waitcnt lgkmcnt(0)
	v_mfma_f32_32x32x16_bf16 v[80:95], v[24:27], v[100:103], v[80:95]
	ds_read_b128 v[24:27], v28 offset:4640
	s_waitcnt lgkmcnt(0)
	v_mfma_f32_32x32x16_bf16 v[64:79], v[24:27], v[100:103], v[64:79]
	ds_read_b128 v[24:27], v28 offset:64
	s_waitcnt lgkmcnt(0)
	v_mfma_f32_32x32x16_bf16 v[80:95], v[24:27], v[104:107], v[80:95]
	ds_read_b128 v[24:27], v28 offset:4672
	s_waitcnt lgkmcnt(0)
	v_mfma_f32_32x32x16_bf16 v[64:79], v[24:27], v[104:107], v[64:79]
	ds_read_b128 v[24:27], v28 offset:96
	s_waitcnt lgkmcnt(0)
	v_mfma_f32_32x32x16_bf16 v[80:95], v[24:27], v[108:111], v[80:95]
	ds_read_b128 v[26:29], v28 offset:4704
	v_mov_b32_e32 v24, v18
	s_waitcnt lgkmcnt(0)
	v_mfma_f32_32x32x16_bf16 v[64:79], v[26:29], v[108:111], v[64:79]
	s_setprio 0

.LBB0_1046:
	s_add_i32 s34, s36, 2
	s_bitcmp1_b32 s36, 0
	s_cselect_b64 s[2:3], -1, 0
	s_and_b64 s[6:7], s[2:3], exec
	s_cselect_b32 s6, 0x3400, 0
	s_add_u32 s66, s36, 1
	v_add_u32_e32 v133, s6, v169
	s_addc_u32 s67, s37, 0
	s_andn2_b32 s6, 1, s36
	s_mulk_i32 s6, 0x2400
	s_waitcnt vmcnt(0)
	ds_write_b128 v133, v[114:117]
	v_add_u32_e32 v114, s6, v168
	ds_write_b128 v114, v[118:121] offset:26624
	s_add_i32 s6, s36, 3
	v_add_u32_e32 v118, s36, v130
	v_lshl_add_u64 v[134:135], v[164:165], 0, s[36:37]
	v_add_u32_e32 v116, 3, v118
	v_lshl_add_u64 v[114:115], v[134:135], 0, 3
	v_cmp_lt_i32_e32 vcc, s6, v201
	v_add_u32_e32 v120, 2, v118
	v_lshl_add_u64 v[118:119], v[134:135], 0, 2
	v_cndmask_b32_e32 v117, 0, v115, vcc
	v_cndmask_b32_e32 v116, v116, v114, vcc
	v_cndmask_b32_e32 v115, v145, v139, vcc
	v_cndmask_b32_e32 v114, v144, v138, vcc
	v_cmp_lt_i32_e32 vcc, s34, v201
	v_mad_u64_u32 v[114:115], s[6:7], v116, s74, v[114:115]
	s_nop 0
	v_cndmask_b32_e32 v121, 0, v119, vcc
	v_cndmask_b32_e32 v120, v120, v118, vcc
	v_cndmask_b32_e32 v119, v163, v141, vcc
	v_cndmask_b32_e32 v118, v162, v140, vcc
	v_mad_u64_u32 v[118:119], s[6:7], v120, s74, v[118:119]
	v_mov_b32_e32 v116, v115
	v_mov_b32_e32 v120, v119
	v_mad_u64_u32 v[116:117], s[6:7], v117, s74, v[116:117]
	v_mad_u64_u32 v[120:121], s[6:7], v121, s74, v[120:121]
	v_mov_b32_e32 v115, v116
	v_mov_b32_e32 v119, v120
	v_lshl_add_u64 v[114:115], v[124:125], 1, v[114:115]
	v_lshl_add_u64 v[118:119], v[128:129], 1, v[118:119]
	v_lshl_add_u64 v[114:115], v[126:127], 1, v[114:115]
	v_lshl_add_u64 v[118:119], v[118:119], 0, v[112:113]
	global_load_dwordx4 v[114:117], v[114:115], off
	v_cmp_lt_i32_e32 vcc, s66, v142
	global_load_dwordx4 v[118:121], v[118:119], off
	s_and_saveexec_b64 s[68:69], vcc
	s_cbranch_execz .LBB0_1052
	v_cmp_ge_i32_e64 s[70:71], s66, v201
	v_cmp_lt_i32_e32 vcc, s66, v201
	s_and_saveexec_b64 s[72:73], vcc
	v_add_u32_e32 v133, 1, v134
	v_cmp_ge_u32_e32 vcc, v133, v170
	v_cmp_lt_u32_e64 s[6:7], v133, v171
	s_and_b64 s[6:7], vcc, s[6:7]
	s_andn2_b64 s[70:71], s[70:71], exec
	s_and_b64 s[6:7], s[6:7], exec
	s_or_b64 s[70:71], s[70:71], s[6:7]
	s_or_b64 exec, exec, s[72:73]
	s_and_saveexec_b64 s[6:7], s[70:71]
	s_cbranch_execz .LBB0_1051
	s_bitcmp1_b32 s66, 0
	s_cselect_b32 s34, 0x3400, 0
	v_add_u32_e32 v133, s34, v181
	ds_read_b128 v[32:35], v133
	ds_read_b128 v[146:149], v133 offset:32
	ds_read_b128 v[48:51], v133 offset:4608
	s_waitcnt lgkmcnt(0)
	s_setprio 1
	v_mfma_f32_32x32x16_bf16 v[32:47], v[32:35], v[96:99], 0
	v_mfma_f32_32x32x16_bf16 v[32:47], v[146:149], v[100:103], v[32:47]
	ds_read_b128 v[146:149], v133 offset:4640
	v_mfma_f32_32x32x16_bf16 v[48:63], v[48:51], v[96:99], 0
	s_waitcnt lgkmcnt(0)
	v_mfma_f32_32x32x16_bf16 v[48:63], v[146:149], v[100:103], v[48:63]
	ds_read_b128 v[146:149], v133 offset:64
	s_waitcnt lgkmcnt(0)
	v_mfma_f32_32x32x16_bf16 v[32:47], v[146:149], v[104:107], v[32:47]
	ds_read_b128 v[146:149], v133 offset:4672
	s_waitcnt lgkmcnt(0)
	v_mfma_f32_32x32x16_bf16 v[48:63], v[146:149], v[104:107], v[48:63]
	ds_read_b128 v[146:149], v133 offset:96
	s_waitcnt lgkmcnt(0)
	v_mfma_f32_32x32x16_bf16 v[32:47], v[146:149], v[108:111], v[32:47]
	ds_read_b128 v[146:149], v133 offset:4704
	s_waitcnt lgkmcnt(0)
	v_mfma_f32_32x32x16_bf16 v[48:63], v[146:149], v[108:111], v[48:63]
	s_setprio 0

.LBB0_1056:
	s_or_b64 exec, exec, s[36:37]
	s_and_saveexec_b64 s[6:7], s[68:69]
	s_cbranch_execz .LBB0_1045
	v_max_f32_e32 v133, v80, v64
	v_max_f32_e32 v134, v81, v65
	s_and_b64 s[2:3], s[2:3], exec
	v_max3_f32 v133, v133, v82, v66
	v_max3_f32 v134, v134, v83, v67
	s_cselect_b32 s2, 0x2400, 0
	v_max3_f32 v133, v133, v84, v68
	v_max3_f32 v134, v134, v85, v69
	s_nop 0
	v_max3_f32 v133, v133, v86, v70
	v_max3_f32 v134, v134, v87, v71
	s_nop 0
	v_max3_f32 v133, v133, v88, v72
	v_max3_f32 v134, v134, v89, v73
	s_nop 0
	v_max3_f32 v133, v133, v90, v74
	v_max3_f32 v134, v134, v91, v75
	s_nop 0
	v_max3_f32 v133, v133, v92, v76
	v_max3_f32 v134, v134, v93, v77
	s_nop 0
	v_max3_f32 v133, v133, v94, v78
	v_max3_f32 v134, v134, v95, v79
	s_nop 0
	v_max_f32_e32 v133, v133, v134
	ds_bpermute_b32 v134, v182, v133
	s_waitcnt lgkmcnt(0)
	v_max_f32_e32 v133, v133, v134
	s_nop 0
	v_max_f32_e32 v133, v210, v133
	s_nop 0
	v_sub_f32_e32 v83, v83, v133
	v_sub_f32_e32 v82, v82, v133
	v_sub_f32_e32 v81, v81, v133
	v_sub_f32_e32 v80, v80, v133
	v_sub_f32_e32 v67, v67, v133
	v_sub_f32_e32 v66, v66, v133
	v_sub_f32_e32 v65, v65, v133
	v_sub_f32_e32 v64, v64, v133
	v_sub_f32_e32 v149, v93, v133
	v_sub_f32_e32 v150, v92, v133
	v_sub_f32_e32 v151, v91, v133
	v_sub_f32_e32 v152, v90, v133
	v_sub_f32_e32 v87, v87, v133
	v_sub_f32_e32 v86, v86, v133
	v_sub_f32_e32 v85, v85, v133
	v_sub_f32_e32 v84, v84, v133
	v_sub_f32_e32 v155, v77, v133
	v_sub_f32_e32 v156, v76, v133
	v_sub_f32_e32 v157, v75, v133
	v_sub_f32_e32 v158, v74, v133
	v_sub_f32_e32 v71, v71, v133
	v_sub_f32_e32 v70, v70, v133
	v_sub_f32_e32 v69, v69, v133
	v_sub_f32_e32 v68, v68, v133
	v_exp_f32_e32 v90, v80
	v_exp_f32_e32 v74, v64
	v_exp_f32_e32 v91, v81
	v_exp_f32_e32 v75, v65
	v_exp_f32_e32 v92, v82
	v_exp_f32_e32 v76, v66
	v_exp_f32_e32 v93, v83
	v_exp_f32_e32 v77, v67
	v_sub_f32_e32 v147, v95, v133
	v_sub_f32_e32 v148, v94, v133
	v_sub_f32_e32 v153, v79, v133
	v_sub_f32_e32 v154, v78, v133
	v_exp_f32_e32 v94, v84
	v_exp_f32_e32 v78, v68
	v_exp_f32_e32 v95, v85
	v_exp_f32_e32 v79, v69
	v_exp_f32_e32 v134, v86
	v_exp_f32_e32 v80, v70
	v_exp_f32_e32 v135, v87
	v_exp_f32_e32 v81, v71
	v_sub_f32_e32 v89, v89, v133
	v_sub_f32_e32 v88, v88, v133
	v_sub_f32_e32 v73, v73, v133
	v_sub_f32_e32 v72, v72, v133
	v_exp_f32_e32 v82, v88
	v_exp_f32_e32 v66, v72
	v_exp_f32_e32 v83, v89
	v_exp_f32_e32 v67, v73
	v_exp_f32_e32 v84, v152
	v_exp_f32_e32 v68, v158
	v_exp_f32_e32 v85, v151
	v_exp_f32_e32 v69, v157
	v_exp_f32_e32 v86, v150
	v_exp_f32_e32 v70, v156
	v_exp_f32_e32 v87, v149
	v_exp_f32_e32 v71, v155
	v_exp_f32_e32 v88, v148
	v_exp_f32_e32 v72, v154
	v_exp_f32_e32 v89, v147
	v_exp_f32_e32 v73, v153
	v_pk_add_f32 v[158:159], v[92:93], v[76:77]
	v_pk_add_f32 v[160:161], v[90:91], v[74:75]
	v_pk_add_f32 v[154:155], v[134:135], v[80:81]
	v_pk_add_f32 v[156:157], v[94:95], v[78:79]
	v_pk_mov_b32 v[166:167], v[160:161], v[158:159] op_sel:[1,0]
	v_mov_b32_e32 v161, v159
	v_pk_add_f32 v[158:159], v[166:167], v[160:161]
	v_pk_mov_b32 v[160:161], v[156:157], v[154:155] op_sel:[1,0]
	v_mov_b32_e32 v157, v155
	v_sub_f32_e32 v146, v210, v133
	v_pk_add_f32 v[154:155], v[160:161], v[156:157]
	v_exp_f32_e32 v64, v146
	v_pk_add_f32 v[146:147], v[88:89], v[72:73]
	v_pk_add_f32 v[148:149], v[86:87], v[70:71]
	v_pk_add_f32 v[150:151], v[84:85], v[68:69]
	v_pk_add_f32 v[152:153], v[82:83], v[66:67]
	v_pk_add_f32 v[158:159], v[158:159], v[158:159] op_sel_hi:[0,1]
	v_pk_add_f32 v[154:155], v[154:155], v[154:155] op_sel_hi:[0,1]
	v_add_f32_e32 v153, v152, v153
	v_add_f32_e32 v151, v150, v151
	v_mov_b32_e32 v152, v148
	v_mov_b32_e32 v150, v149
	v_mov_b32_e32 v158, v146
	v_mov_b32_e32 v154, v147
	v_pk_add_f32 v[148:149], v[152:153], v[150:151]
	v_pk_add_f32 v[146:147], v[158:159], v[154:155]
	v_add_u32_e32 v154, s2, v183
	v_pk_add_f32 v[146:147], v[148:149], v[146:147]
	v_cvt_pk_bf16_f32 v90, v90, v91
	v_add_f32_e32 v65, v146, v147
	ds_read_b64_tr_b16 v[146:147], v154 offset:26624
	ds_read_b64_tr_b16 v[148:149], v154 offset:27776
	ds_read_b64_tr_b16 v[150:151], v154 offset:26688
	ds_read_b64_tr_b16 v[152:153], v154 offset:27840
	v_pk_mul_f32 v[14:15], v[14:15], v[64:65] op_sel_hi:[1,0]
	v_pk_mul_f32 v[12:13], v[12:13], v[64:65] op_sel_hi:[1,0]
	v_pk_mul_f32 v[10:11], v[10:11], v[64:65] op_sel_hi:[1,0]
	v_pk_mul_f32 v[8:9], v[8:9], v[64:65] op_sel_hi:[1,0]
	v_pk_mul_f32 v[6:7], v[6:7], v[64:65] op_sel_hi:[1,0]
	v_pk_mul_f32 v[4:5], v[4:5], v[64:65] op_sel_hi:[1,0]
	v_pk_mul_f32 v[2:3], v[2:3], v[64:65] op_sel_hi:[1,0]
	v_pk_mul_f32 v[0:1], v[0:1], v[64:65] op_sel_hi:[1,0]
	v_pk_mul_f32 v[30:31], v[30:31], v[64:65] op_sel_hi:[1,0]
	v_pk_mul_f32 v[28:29], v[28:29], v[64:65] op_sel_hi:[1,0]
	v_pk_mul_f32 v[26:27], v[26:27], v[64:65] op_sel_hi:[1,0]
	v_pk_mul_f32 v[24:25], v[24:25], v[64:65] op_sel_hi:[1,0]
	v_pk_mul_f32 v[22:23], v[22:23], v[64:65] op_sel_hi:[1,0]
	v_pk_mul_f32 v[20:21], v[20:21], v[64:65] op_sel_hi:[1,0]
	v_pk_mul_f32 v[18:19], v[18:19], v[64:65] op_sel_hi:[1,0]
	v_pk_mul_f32 v[16:17], v[16:17], v[64:65] op_sel_hi:[1,0]
	v_cvt_pk_bf16_f32 v91, v92, v93
	v_cvt_pk_bf16_f32 v92, v94, v95
	v_cvt_pk_bf16_f32 v93, v134, v135
	v_cvt_pk_bf16_f32 v82, v82, v83
	v_cvt_pk_bf16_f32 v83, v84, v85
	s_waitcnt lgkmcnt(0)
	s_setprio 1
	v_mfma_f32_32x32x16_bf16 v[0:15], v[146:149], v[90:93], v[0:15]
	s_setprio 0
	v_cvt_pk_bf16_f32 v84, v86, v87
	v_cvt_pk_bf16_f32 v85, v88, v89
	v_cvt_pk_bf16_f32 v74, v74, v75
	v_cvt_pk_bf16_f32 v75, v76, v77
	v_cvt_pk_bf16_f32 v76, v78, v79
	v_cvt_pk_bf16_f32 v77, v80, v81
	v_cvt_pk_bf16_f32 v66, v66, v67
	s_setprio 1
	v_mfma_f32_32x32x16_bf16 v[16:31], v[150:153], v[90:93], v[16:31]
	s_setprio 0
	ds_read_b64_tr_b16 v[86:87], v154 offset:28928
	ds_read_b64_tr_b16 v[88:89], v154 offset:30080
	ds_read_b64_tr_b16 v[90:91], v154 offset:28992
	ds_read_b64_tr_b16 v[92:93], v154 offset:30144
	v_cvt_pk_bf16_f32 v67, v68, v69
	v_cvt_pk_bf16_f32 v68, v70, v71
	v_cvt_pk_bf16_f32 v69, v72, v73
	ds_bpermute_b32 v166, v182, v65
	v_mov_b32_e32 v210, v133
	s_waitcnt lgkmcnt(0)
	v_add_f32_e32 v65, v65, v166
	s_setprio 1
	v_mfma_f32_32x32x16_bf16 v[0:15], v[86:89], v[82:85], v[0:15]
	v_fmac_f32_e32 v65, v143, v64
	v_mov_b32_e32 v143, v65
	v_mfma_f32_32x32x16_bf16 v[16:31], v[90:93], v[82:85], v[16:31]
	s_setprio 0
	ds_read_b64_tr_b16 v[78:79], v154 offset:31232
	ds_read_b64_tr_b16 v[80:81], v154 offset:32384
	ds_read_b64_tr_b16 v[82:83], v154 offset:31296
	ds_read_b64_tr_b16 v[84:85], v154 offset:32448
	s_waitcnt lgkmcnt(0)
	s_setprio 1
	v_mfma_f32_32x32x16_bf16 v[0:15], v[78:81], v[74:77], v[0:15]
	v_mfma_f32_32x32x16_bf16 v[16:31], v[82:85], v[74:77], v[16:31]
	s_setprio 0
	ds_read_b64_tr_b16 v[70:71], v154 offset:33536
	ds_read_b64_tr_b16 v[72:73], v154 offset:34688
	ds_read_b64_tr_b16 v[74:75], v154 offset:33600
	ds_read_b64_tr_b16 v[76:77], v154 offset:34752
	s_waitcnt lgkmcnt(0)
	s_setprio 1
	v_mfma_f32_32x32x16_bf16 v[0:15], v[70:73], v[66:69], v[0:15]
	v_mfma_f32_32x32x16_bf16 v[16:31], v[74:77], v[66:69], v[16:31]
	s_setprio 0
	s_branch .LBB0_1045

.LBB0_1071:
	v_cmp_ge_i32_e64 s[8:9], v165, v201
	v_cmp_lt_i32_e32 vcc, v165, v201
	s_and_saveexec_b64 s[36:37], vcc
	v_add3_u32 v146, v132, s68, -2
	v_cmp_ge_u32_e32 vcc, v146, v170
	v_cmp_lt_u32_e64 s[6:7], v146, v171
	s_and_b64 s[6:7], vcc, s[6:7]
	s_andn2_b64 s[8:9], s[8:9], exec
	s_and_b64 s[6:7], s[6:7], exec
	s_or_b64 s[8:9], s[8:9], s[6:7]
	s_or_b64 exec, exec, s[36:37]
	s_and_saveexec_b64 s[6:7], s[8:9]
	s_cbranch_execz .LBB0_1075
	v_and_b32_e32 v32, 1, v165
	v_cmp_eq_u32_e32 vcc, 1, v32
	s_nop 1
	v_cndmask_b32_e32 v32, 0, v197, vcc
	v_add_u32_e32 v150, v181, v32
	ds_read_b128 v[32:35], v150
	ds_read_b128 v[146:149], v150 offset:32
	ds_read_b128 v[48:51], v150 offset:4608
	s_waitcnt lgkmcnt(0)
	s_setprio 1
	v_mfma_f32_32x32x16_bf16 v[32:47], v[32:35], v[96:99], 0
	v_mfma_f32_32x32x16_bf16 v[32:47], v[146:149], v[100:103], v[32:47]
	ds_read_b128 v[146:149], v150 offset:4640
	v_mfma_f32_32x32x16_bf16 v[48:63], v[48:51], v[96:99], 0
	s_waitcnt lgkmcnt(0)
	v_mfma_f32_32x32x16_bf16 v[48:63], v[146:149], v[100:103], v[48:63]
	ds_read_b128 v[146:149], v150 offset:64
	s_waitcnt lgkmcnt(0)
	v_mfma_f32_32x32x16_bf16 v[32:47], v[146:149], v[104:107], v[32:47]
	ds_read_b128 v[146:149], v150 offset:4672
	s_waitcnt lgkmcnt(0)
	v_mfma_f32_32x32x16_bf16 v[48:63], v[146:149], v[104:107], v[48:63]
	ds_read_b128 v[146:149], v150 offset:96
	s_waitcnt lgkmcnt(0)
	v_mfma_f32_32x32x16_bf16 v[32:47], v[146:149], v[108:111], v[32:47]
	ds_read_b128 v[146:149], v150 offset:4704
	s_waitcnt lgkmcnt(0)
	v_mfma_f32_32x32x16_bf16 v[48:63], v[146:149], v[108:111], v[48:63]
	s_setprio 0

.LBB0_1080:
	s_or_b64 exec, exec, s[2:3]
	s_and_saveexec_b64 s[2:3], s[6:7]
	s_cbranch_execz .LBB0_1061
	v_max_f32_e32 v146, v80, v64
	v_max_f32_e32 v147, v81, v65
	v_cmp_eq_u32_e32 vcc, 1, v167
	v_max3_f32 v146, v146, v82, v66
	v_max3_f32 v147, v147, v83, v67
	s_nop 0
	v_max3_f32 v146, v146, v84, v68
	v_max3_f32 v147, v147, v85, v69
	s_nop 0
	v_max3_f32 v146, v146, v86, v70
	v_max3_f32 v147, v147, v87, v71
	s_nop 0
	v_max3_f32 v146, v146, v88, v72
	v_max3_f32 v147, v147, v89, v73
	s_nop 0
	v_max3_f32 v146, v146, v90, v74
	v_max3_f32 v147, v147, v91, v75
	s_nop 0
	v_max3_f32 v146, v146, v92, v76
	v_max3_f32 v147, v147, v93, v77
	s_nop 0
	v_max3_f32 v146, v146, v94, v78
	v_max3_f32 v147, v147, v95, v79
	s_nop 0
	v_max_f32_e32 v146, v146, v147
	ds_bpermute_b32 v147, v182, v146
	s_waitcnt lgkmcnt(0)
	v_max_f32_e32 v146, v146, v147
	s_nop 0
	v_max_f32_e32 v166, v210, v146
	s_nop 0
	v_sub_f32_e32 v83, v83, v166
	v_sub_f32_e32 v82, v82, v166
	v_sub_f32_e32 v81, v81, v166
	v_sub_f32_e32 v80, v80, v166
	v_sub_f32_e32 v67, v67, v166
	v_sub_f32_e32 v66, v66, v166
	v_sub_f32_e32 v65, v65, v166
	v_sub_f32_e32 v64, v64, v166
	v_sub_f32_e32 v149, v93, v166
	v_sub_f32_e32 v150, v92, v166
	v_sub_f32_e32 v151, v91, v166
	v_sub_f32_e32 v152, v90, v166
	v_sub_f32_e32 v87, v87, v166
	v_sub_f32_e32 v86, v86, v166
	v_sub_f32_e32 v85, v85, v166
	v_sub_f32_e32 v84, v84, v166
	v_sub_f32_e32 v155, v77, v166
	v_sub_f32_e32 v156, v76, v166
	v_sub_f32_e32 v157, v75, v166
	v_sub_f32_e32 v158, v74, v166
	v_sub_f32_e32 v71, v71, v166
	v_sub_f32_e32 v70, v70, v166
	v_sub_f32_e32 v69, v69, v166
	v_sub_f32_e32 v68, v68, v166
	v_exp_f32_e32 v90, v80
	v_exp_f32_e32 v74, v64
	v_exp_f32_e32 v91, v81
	v_exp_f32_e32 v75, v65
	v_exp_f32_e32 v92, v82
	v_exp_f32_e32 v76, v66
	v_exp_f32_e32 v93, v83
	v_exp_f32_e32 v77, v67
	v_sub_f32_e32 v147, v95, v166
	v_sub_f32_e32 v148, v94, v166
	v_sub_f32_e32 v153, v79, v166
	v_sub_f32_e32 v154, v78, v166
	v_exp_f32_e32 v94, v84
	v_exp_f32_e32 v78, v68
	v_exp_f32_e32 v95, v85
	v_exp_f32_e32 v79, v69
	v_exp_f32_e32 v164, v86
	v_exp_f32_e32 v80, v70
	v_exp_f32_e32 v165, v87
	v_exp_f32_e32 v81, v71
	v_sub_f32_e32 v89, v89, v166
	v_sub_f32_e32 v88, v88, v166
	v_sub_f32_e32 v73, v73, v166
	v_sub_f32_e32 v72, v72, v166
	v_exp_f32_e32 v82, v88
	v_exp_f32_e32 v66, v72
	v_exp_f32_e32 v83, v89
	v_exp_f32_e32 v67, v73
	v_exp_f32_e32 v84, v152
	v_exp_f32_e32 v68, v158
	v_exp_f32_e32 v85, v151
	v_exp_f32_e32 v69, v157
	v_exp_f32_e32 v86, v150
	v_exp_f32_e32 v70, v156
	v_exp_f32_e32 v87, v149
	v_exp_f32_e32 v71, v155
	v_exp_f32_e32 v88, v148
	v_exp_f32_e32 v72, v154
	v_exp_f32_e32 v89, v147
	v_exp_f32_e32 v73, v153
	v_pk_add_f32 v[158:159], v[92:93], v[76:77]
	v_pk_add_f32 v[160:161], v[90:91], v[74:75]
	v_pk_add_f32 v[154:155], v[164:165], v[80:81]
	v_pk_add_f32 v[156:157], v[94:95], v[78:79]
	v_pk_mov_b32 v[184:185], v[160:161], v[158:159] op_sel:[1,0]
	v_mov_b32_e32 v161, v159
	v_pk_add_f32 v[158:159], v[184:185], v[160:161]
	v_pk_mov_b32 v[160:161], v[156:157], v[154:155] op_sel:[1,0]
	v_mov_b32_e32 v157, v155
	v_sub_f32_e32 v146, v210, v166
	v_pk_add_f32 v[154:155], v[160:161], v[156:157]
	v_exp_f32_e32 v64, v146
	v_pk_add_f32 v[146:147], v[88:89], v[72:73]
	v_pk_add_f32 v[148:149], v[86:87], v[70:71]
	v_pk_add_f32 v[150:151], v[84:85], v[68:69]
	v_pk_add_f32 v[152:153], v[82:83], v[66:67]
	v_pk_add_f32 v[158:159], v[158:159], v[158:159] op_sel_hi:[0,1]
	v_pk_add_f32 v[154:155], v[154:155], v[154:155] op_sel_hi:[0,1]
	v_add_f32_e32 v153, v152, v153
	v_add_f32_e32 v151, v150, v151
	v_mov_b32_e32 v152, v148
	v_mov_b32_e32 v150, v149
	v_mov_b32_e32 v158, v146
	v_mov_b32_e32 v154, v147
	v_pk_add_f32 v[148:149], v[152:153], v[150:151]
	v_pk_add_f32 v[146:147], v[158:159], v[154:155]
	v_cvt_pk_bf16_f32 v90, v90, v91
	v_pk_add_f32 v[146:147], v[148:149], v[146:147]
	v_cvt_pk_bf16_f32 v91, v92, v93
	v_add_f32_e32 v65, v146, v147
	v_cndmask_b32_e32 v146, 0, v228, vcc
	v_add_u32_e32 v154, v183, v146
	ds_read_b64_tr_b16 v[146:147], v154 offset:26624
	ds_read_b64_tr_b16 v[148:149], v154 offset:27776
	ds_read_b64_tr_b16 v[150:151], v154 offset:26688
	ds_read_b64_tr_b16 v[152:153], v154 offset:27840
	v_pk_mul_f32 v[14:15], v[14:15], v[64:65] op_sel_hi:[1,0]
	v_pk_mul_f32 v[12:13], v[12:13], v[64:65] op_sel_hi:[1,0]
	v_pk_mul_f32 v[10:11], v[10:11], v[64:65] op_sel_hi:[1,0]
	v_pk_mul_f32 v[8:9], v[8:9], v[64:65] op_sel_hi:[1,0]
	v_pk_mul_f32 v[6:7], v[6:7], v[64:65] op_sel_hi:[1,0]
	v_pk_mul_f32 v[4:5], v[4:5], v[64:65] op_sel_hi:[1,0]
	v_pk_mul_f32 v[2:3], v[2:3], v[64:65] op_sel_hi:[1,0]
	v_pk_mul_f32 v[0:1], v[0:1], v[64:65] op_sel_hi:[1,0]
	v_pk_mul_f32 v[30:31], v[30:31], v[64:65] op_sel_hi:[1,0]
	v_pk_mul_f32 v[28:29], v[28:29], v[64:65] op_sel_hi:[1,0]
	v_pk_mul_f32 v[26:27], v[26:27], v[64:65] op_sel_hi:[1,0]
	v_pk_mul_f32 v[24:25], v[24:25], v[64:65] op_sel_hi:[1,0]
	v_pk_mul_f32 v[22:23], v[22:23], v[64:65] op_sel_hi:[1,0]
	v_pk_mul_f32 v[20:21], v[20:21], v[64:65] op_sel_hi:[1,0]
	v_pk_mul_f32 v[18:19], v[18:19], v[64:65] op_sel_hi:[1,0]
	v_pk_mul_f32 v[16:17], v[16:17], v[64:65] op_sel_hi:[1,0]
	v_cvt_pk_bf16_f32 v92, v94, v95
	v_cvt_pk_bf16_f32 v93, v164, v165
	v_cvt_pk_bf16_f32 v82, v82, v83
	v_cvt_pk_bf16_f32 v83, v84, v85
	s_waitcnt lgkmcnt(0)
	s_setprio 1
	v_mfma_f32_32x32x16_bf16 v[0:15], v[146:149], v[90:93], v[0:15]
	s_setprio 0
	v_cvt_pk_bf16_f32 v84, v86, v87
	v_cvt_pk_bf16_f32 v85, v88, v89
	v_cvt_pk_bf16_f32 v74, v74, v75
	v_cvt_pk_bf16_f32 v75, v76, v77
	v_cvt_pk_bf16_f32 v76, v78, v79
	v_cvt_pk_bf16_f32 v77, v80, v81
	v_cvt_pk_bf16_f32 v66, v66, v67
	s_setprio 1
	v_mfma_f32_32x32x16_bf16 v[16:31], v[150:153], v[90:93], v[16:31]
	s_setprio 0
	ds_read_b64_tr_b16 v[86:87], v154 offset:28928
	ds_read_b64_tr_b16 v[88:89], v154 offset:30080
	ds_read_b64_tr_b16 v[90:91], v154 offset:28992
	ds_read_b64_tr_b16 v[92:93], v154 offset:30144
	v_cvt_pk_bf16_f32 v67, v68, v69
	v_cvt_pk_bf16_f32 v68, v70, v71
	v_cvt_pk_bf16_f32 v69, v72, v73
	ds_bpermute_b32 v210, v182, v65
	s_waitcnt lgkmcnt(0)
	v_add_f32_e32 v65, v65, v210
	s_setprio 1
	v_mfma_f32_32x32x16_bf16 v[0:15], v[86:89], v[82:85], v[0:15]
	v_fmac_f32_e32 v65, v143, v64
	v_mov_b32_e32 v143, v65
	v_mov_b32_e32 v210, v166
	v_mfma_f32_32x32x16_bf16 v[16:31], v[90:93], v[82:85], v[16:31]
	s_setprio 0
	ds_read_b64_tr_b16 v[78:79], v154 offset:31232
	ds_read_b64_tr_b16 v[80:81], v154 offset:32384
	ds_read_b64_tr_b16 v[82:83], v154 offset:31296
	ds_read_b64_tr_b16 v[84:85], v154 offset:32448
	s_waitcnt lgkmcnt(0)
	s_setprio 1
	v_mfma_f32_32x32x16_bf16 v[0:15], v[78:81], v[74:77], v[0:15]
	v_mfma_f32_32x32x16_bf16 v[16:31], v[82:85], v[74:77], v[16:31]
	s_setprio 0
	ds_read_b64_tr_b16 v[70:71], v154 offset:33536
	ds_read_b64_tr_b16 v[72:73], v154 offset:34688
	ds_read_b64_tr_b16 v[74:75], v154 offset:33600
	ds_read_b64_tr_b16 v[76:77], v154 offset:34752
	s_waitcnt lgkmcnt(0)
	s_setprio 1
	v_mfma_f32_32x32x16_bf16 v[0:15], v[70:73], v[66:69], v[0:15]
	v_mfma_f32_32x32x16_bf16 v[16:31], v[74:77], v[66:69], v[16:31]
	s_setprio 0
	s_branch .LBB0_1061

.LBB0_1102:
	s_or_b64 exec, exec, s[2:3]
	v_mov_b32_e32 v14, v113
	v_mov_b32_e32 v15, v113
	v_mov_b32_e32 v0, v113
	v_mov_b32_e32 v1, v113
	v_mov_b32_e32 v2, v113
	v_mov_b32_e32 v3, v113
	v_mov_b32_e32 v4, v113
	v_mov_b32_e32 v5, v113
	v_mov_b32_e32 v6, v113
	v_mov_b32_e32 v7, v113
	v_mov_b32_e32 v8, v113
	v_mov_b32_e32 v9, v113
	v_mov_b32_e32 v10, v113
	v_mov_b32_e32 v11, v113
	v_mov_b32_e32 v12, v113
	v_mov_b32_e32 v13, v113
	v_mov_b64_e32 v[110:111], v[14:15]
	v_mov_b64_e32 v[94:95], v[14:15]
	v_xor_b32_e32 v16, 0x80000000, v16
	v_mov_b64_e32 v[108:109], v[12:13]
	v_mov_b64_e32 v[106:107], v[10:11]
	v_mov_b64_e32 v[104:105], v[8:9]
	v_mov_b64_e32 v[102:103], v[6:7]
	v_mov_b64_e32 v[100:101], v[4:5]
	v_mov_b64_e32 v[98:99], v[2:3]
	v_mov_b64_e32 v[96:97], v[0:1]
	v_mov_b64_e32 v[92:93], v[12:13]
	v_mov_b64_e32 v[90:91], v[10:11]
	v_mov_b64_e32 v[88:89], v[8:9]
	v_mov_b64_e32 v[86:87], v[6:7]
	v_mov_b64_e32 v[84:85], v[4:5]
	v_mov_b64_e32 v[82:83], v[2:3]
	v_mov_b64_e32 v[80:81], v[0:1]
	s_and_saveexec_b64 s[2:3], s[8:9]
	s_cbranch_execz .LBB0_1104
	v_mul_u32_u24_e32 v37, 0x90, v32
	v_add3_u32 v39, 0, v37, v34
	ds_read_b128 v[40:43], v39
	v_mov_b32_e32 v30, v16
	v_mov_b32_e32 v31, v16
	v_mov_b32_e32 v17, v16
	v_mov_b32_e32 v18, v16
	v_mov_b32_e32 v19, v16
	v_mov_b32_e32 v20, v16
	v_mov_b32_e32 v21, v16
	v_mov_b32_e32 v22, v16
	v_mov_b32_e32 v23, v16
	v_mov_b32_e32 v24, v16
	v_mov_b32_e32 v25, v16
	v_mov_b32_e32 v26, v16
	v_mov_b32_e32 v27, v16
	v_mov_b32_e32 v28, v16
	v_mov_b32_e32 v29, v16
	v_mov_b64_e32 v[94:95], v[30:31]
	v_mov_b64_e32 v[92:93], v[28:29]
	s_waitcnt lgkmcnt(0)
	s_setprio 1
	v_mfma_f32_32x32x16_bf16 v[96:111], v[40:43], v[114:117], v[16:31]
	s_setprio 0
	ds_read_b128 v[40:43], v39 offset:4608
	v_mov_b64_e32 v[90:91], v[26:27]
	v_mov_b64_e32 v[88:89], v[24:25]
	v_mov_b64_e32 v[86:87], v[22:23]
	v_mov_b64_e32 v[84:85], v[20:21]
	v_mov_b64_e32 v[82:83], v[18:19]
	v_mov_b64_e32 v[80:81], v[16:17]
	ds_read_b128 v[18:21], v39 offset:32
	s_waitcnt lgkmcnt(0)
	s_setprio 1
	v_mfma_f32_32x32x16_bf16 v[96:111], v[18:21], v[118:121], v[96:111]
	ds_read_b128 v[18:21], v39 offset:4640
	v_mov_b32_e32 v17, v34
	v_mfma_f32_32x32x16_bf16 v[80:95], v[40:43], v[114:117], v[80:95]
	s_waitcnt lgkmcnt(0)
	v_mfma_f32_32x32x16_bf16 v[80:95], v[18:21], v[118:121], v[80:95]
	ds_read_b128 v[18:21], v39 offset:64
	s_waitcnt lgkmcnt(0)
	v_mfma_f32_32x32x16_bf16 v[96:111], v[18:21], v[122:125], v[96:111]
	ds_read_b128 v[18:21], v39 offset:4672
	s_waitcnt lgkmcnt(0)
	v_mfma_f32_32x32x16_bf16 v[80:95], v[18:21], v[122:125], v[80:95]
	ds_read_b128 v[18:21], v39 offset:96
	s_waitcnt lgkmcnt(0)
	v_mfma_f32_32x32x16_bf16 v[96:111], v[18:21], v[126:129], v[96:111]
	ds_read_b128 v[18:21], v39 offset:4704
	s_waitcnt lgkmcnt(0)
	v_mfma_f32_32x32x16_bf16 v[80:95], v[18:21], v[126:129], v[80:95]
	s_setprio 0

.LBB0_1107:
	s_add_i32 s34, s36, 2
	s_bitcmp1_b32 s36, 0
	s_cselect_b64 s[2:3], -1, 0
	s_and_b64 s[6:7], s[2:3], exec
	s_cselect_b32 s6, 0x3400, 0
	s_add_u32 s66, s36, 1
	v_add_u32_e32 v146, s6, v204
	s_addc_u32 s67, s37, 0
	s_andn2_b32 s6, 1, s36
	s_mulk_i32 s6, 0x2400
	s_waitcnt vmcnt(0)
	ds_write_b128 v146, v[130:133]
	v_add_u32_e32 v130, s6, v203
	ds_write_b128 v130, v[134:137] offset:26624
	s_add_i32 s6, s36, 3
	v_add_u32_e32 v134, s36, v174
	v_lshl_add_u64 v[178:179], v[164:165], 0, s[36:37]
	v_add_u32_e32 v132, 3, v134
	v_lshl_add_u64 v[130:131], v[178:179], 0, 3
	v_cmp_lt_i32_e32 vcc, s6, v201
	v_add_u32_e32 v136, 2, v134
	v_lshl_add_u64 v[134:135], v[178:179], 0, 2
	v_cndmask_b32_e32 v133, 0, v131, vcc
	v_cndmask_b32_e32 v132, v132, v130, vcc
	v_cndmask_b32_e32 v131, v145, v139, vcc
	v_cndmask_b32_e32 v130, v144, v138, vcc
	v_cmp_lt_i32_e32 vcc, s34, v201
	v_mad_u64_u32 v[130:131], s[6:7], v132, s74, v[130:131]
	s_nop 0
	v_cndmask_b32_e32 v137, 0, v135, vcc
	v_cndmask_b32_e32 v136, v136, v134, vcc
	v_cndmask_b32_e32 v135, v163, v141, vcc
	v_cndmask_b32_e32 v134, v162, v140, vcc
	v_mad_u64_u32 v[134:135], s[6:7], v136, s74, v[134:135]
	v_mov_b32_e32 v132, v131
	v_mov_b32_e32 v136, v135
	v_mad_u64_u32 v[132:133], s[6:7], v133, s74, v[132:133]
	v_mad_u64_u32 v[136:137], s[6:7], v137, s74, v[136:137]
	v_mov_b32_e32 v131, v132
	v_mov_b32_e32 v135, v136
	v_lshl_add_u64 v[130:131], v[168:169], 1, v[130:131]
	v_lshl_add_u64 v[134:135], v[172:173], 1, v[134:135]
	v_lshl_add_u64 v[130:131], v[170:171], 1, v[130:131]
	v_lshl_add_u64 v[134:135], v[134:135], 0, v[112:113]
	global_load_dwordx4 v[130:133], v[130:131], off
	v_cmp_lt_i32_e32 vcc, s66, v142
	global_load_dwordx4 v[134:137], v[134:135], off
	s_and_saveexec_b64 s[68:69], vcc
	s_cbranch_execz .LBB0_1113
	v_cmp_ge_i32_e64 s[70:71], s66, v201
	v_cmp_lt_i32_e32 vcc, s66, v201
	s_and_saveexec_b64 s[72:73], vcc
	v_add_u32_e32 v146, 1, v178
	v_cmp_ge_u32_e32 vcc, v146, v205
	v_cmp_lt_u32_e64 s[6:7], v146, v206
	s_and_b64 s[6:7], vcc, s[6:7]
	s_andn2_b64 s[70:71], s[70:71], exec
	s_and_b64 s[6:7], s[6:7], exec
	s_or_b64 s[70:71], s[70:71], s[6:7]
	s_or_b64 exec, exec, s[72:73]
	s_and_saveexec_b64 s[6:7], s[70:71]
	s_cbranch_execz .LBB0_1112
	s_bitcmp1_b32 s66, 0
	s_cselect_b32 s34, 0x3400, 0
	v_add_u32_e32 v150, s34, v216
	ds_read_b128 v[64:67], v150
	ds_read_b128 v[146:149], v150 offset:4608
	s_waitcnt lgkmcnt(0)
	s_setprio 1
	v_mfma_f32_32x32x16_bf16 v[48:63], v[64:67], v[114:117], v[16:31]
	v_mfma_f32_32x32x16_bf16 v[64:79], v[146:149], v[114:117], v[16:31]
	ds_read_b128 v[146:149], v150 offset:32
	s_waitcnt lgkmcnt(0)
	v_mfma_f32_32x32x16_bf16 v[48:63], v[146:149], v[118:121], v[48:63]
	ds_read_b128 v[146:149], v150 offset:4640
	s_waitcnt lgkmcnt(0)
	v_mfma_f32_32x32x16_bf16 v[64:79], v[146:149], v[118:121], v[64:79]
	ds_read_b128 v[146:149], v150 offset:64
	s_waitcnt lgkmcnt(0)
	v_mfma_f32_32x32x16_bf16 v[48:63], v[146:149], v[122:125], v[48:63]
	ds_read_b128 v[146:149], v150 offset:4672
	s_waitcnt lgkmcnt(0)
	v_mfma_f32_32x32x16_bf16 v[64:79], v[146:149], v[122:125], v[64:79]
	ds_read_b128 v[146:149], v150 offset:96
	s_waitcnt lgkmcnt(0)
	v_mfma_f32_32x32x16_bf16 v[48:63], v[146:149], v[126:129], v[48:63]
	ds_read_b128 v[146:149], v150 offset:4704
	s_waitcnt lgkmcnt(0)
	v_mfma_f32_32x32x16_bf16 v[64:79], v[146:149], v[126:129], v[64:79]
	s_setprio 0

.LBB0_1117:
	s_or_b64 exec, exec, s[36:37]
	s_and_saveexec_b64 s[6:7], s[68:69]
	s_cbranch_execz .LBB0_1106
	v_exp_f32_e32 v146, v96
	v_exp_f32_e32 v96, v80
	v_exp_f32_e32 v147, v97
	v_exp_f32_e32 v97, v81
	v_exp_f32_e32 v148, v98
	v_exp_f32_e32 v98, v82
	v_exp_f32_e32 v149, v99
	v_exp_f32_e32 v99, v83
	v_exp_f32_e32 v150, v100
	v_exp_f32_e32 v100, v84
	v_exp_f32_e32 v151, v101
	v_exp_f32_e32 v101, v85
	v_exp_f32_e32 v152, v102
	v_exp_f32_e32 v102, v86
	v_exp_f32_e32 v153, v103
	v_exp_f32_e32 v103, v87
	v_exp_f32_e32 v104, v104
	v_exp_f32_e32 v80, v88
	v_exp_f32_e32 v105, v105
	v_exp_f32_e32 v81, v89
	v_exp_f32_e32 v88, v106
	v_exp_f32_e32 v82, v90
	v_exp_f32_e32 v89, v107
	v_exp_f32_e32 v83, v91
	v_exp_f32_e32 v90, v108
	v_exp_f32_e32 v84, v92
	v_exp_f32_e32 v91, v109
	v_exp_f32_e32 v85, v93
	v_exp_f32_e32 v110, v110
	v_exp_f32_e32 v86, v94
	v_exp_f32_e32 v111, v111
	v_exp_f32_e32 v87, v95
	v_pk_add_f32 v[158:159], v[148:149], v[98:99]
	v_pk_add_f32 v[160:161], v[146:147], v[96:97]
	v_pk_add_f32 v[154:155], v[152:153], v[102:103]
	v_pk_add_f32 v[156:157], v[150:151], v[100:101]
	v_pk_mov_b32 v[178:179], v[160:161], v[158:159] op_sel:[1,0]
	v_mov_b32_e32 v161, v159
	v_pk_add_f32 v[158:159], v[178:179], v[160:161]
	v_pk_mov_b32 v[160:161], v[156:157], v[154:155] op_sel:[1,0]
	v_mov_b32_e32 v157, v155
	v_pk_add_f32 v[154:155], v[160:161], v[156:157]
	v_pk_add_f32 v[92:93], v[110:111], v[86:87]
	v_pk_add_f32 v[94:95], v[90:91], v[84:85]
	v_pk_add_f32 v[106:107], v[88:89], v[82:83]
	v_pk_add_f32 v[108:109], v[104:105], v[80:81]
	v_pk_add_f32 v[158:159], v[158:159], v[158:159] op_sel_hi:[0,1]
	v_pk_add_f32 v[154:155], v[154:155], v[154:155] op_sel_hi:[0,1]
	v_add_f32_e32 v109, v108, v109
	v_add_f32_e32 v107, v106, v107
	v_mov_b32_e32 v108, v94
	v_mov_b32_e32 v106, v95
	v_mov_b32_e32 v158, v92
	v_mov_b32_e32 v154, v93
	v_pk_add_f32 v[94:95], v[108:109], v[106:107]
	v_pk_add_f32 v[92:93], v[158:159], v[154:155]
	s_and_b64 s[2:3], s[2:3], exec
	v_pk_add_f32 v[92:93], v[94:95], v[92:93]
	s_cselect_b32 s2, 0x2400, 0
	v_add_f32_e32 v92, v92, v93
	v_add_u32_e32 v93, s2, v217
	v_cvt_pk_bf16_f32 v106, v146, v147
	v_cvt_pk_bf16_f32 v107, v148, v149
	v_cvt_pk_bf16_f32 v108, v150, v151
	v_cvt_pk_bf16_f32 v109, v152, v153
	ds_read_b64_tr_b16 v[146:147], v93 offset:26624
	ds_read_b64_tr_b16 v[148:149], v93 offset:27776
	ds_read_b64_tr_b16 v[150:151], v93 offset:26688
	ds_read_b64_tr_b16 v[152:153], v93 offset:27840
	s_waitcnt lgkmcnt(0)
	s_setprio 1
	v_mfma_f32_32x32x16_bf16 v[0:15], v[146:149], v[106:109], v[0:15]
	s_setprio 0
	v_cvt_pk_bf16_f32 v104, v104, v105
	v_cvt_pk_bf16_f32 v105, v88, v89
	v_cvt_pk_bf16_f32 v80, v80, v81
	v_cvt_pk_bf16_f32 v81, v82, v83
	v_cvt_pk_bf16_f32 v82, v84, v85
	v_cvt_pk_bf16_f32 v83, v86, v87
	v_add_f32_e32 v143, v143, v92
	s_setprio 1
	v_mfma_f32_32x32x16_bf16 v[32:47], v[150:153], v[106:109], v[32:47]
	s_setprio 0
	v_cvt_pk_bf16_f32 v106, v90, v91
	v_cvt_pk_bf16_f32 v107, v110, v111
	ds_read_b64_tr_b16 v[88:89], v93 offset:28928
	ds_read_b64_tr_b16 v[90:91], v93 offset:30080
	ds_read_b64_tr_b16 v[108:109], v93 offset:28992
	ds_read_b64_tr_b16 v[110:111], v93 offset:30144
	s_waitcnt lgkmcnt(0)
	s_setprio 1
	v_mfma_f32_32x32x16_bf16 v[0:15], v[88:91], v[104:107], v[0:15]
	s_setprio 0
	v_cvt_pk_bf16_f32 v88, v96, v97
	v_cvt_pk_bf16_f32 v89, v98, v99
	v_cvt_pk_bf16_f32 v90, v100, v101
	ds_read_b64_tr_b16 v[94:95], v93 offset:31232
	ds_read_b64_tr_b16 v[96:97], v93 offset:32384
	ds_read_b64_tr_b16 v[98:99], v93 offset:31296
	ds_read_b64_tr_b16 v[100:101], v93 offset:32448
	v_cvt_pk_bf16_f32 v91, v102, v103
	s_setprio 1
	v_mfma_f32_32x32x16_bf16 v[32:47], v[108:111], v[104:107], v[32:47]
	s_waitcnt lgkmcnt(0)
	v_mfma_f32_32x32x16_bf16 v[0:15], v[94:97], v[88:91], v[0:15]
	v_mfma_f32_32x32x16_bf16 v[32:47], v[98:101], v[88:91], v[32:47]
	s_setprio 0
	ds_read_b64_tr_b16 v[84:85], v93 offset:33536
	ds_read_b64_tr_b16 v[86:87], v93 offset:34688
	ds_read_b64_tr_b16 v[88:89], v93 offset:33600
	ds_read_b64_tr_b16 v[90:91], v93 offset:34752
	s_waitcnt lgkmcnt(0)
	s_setprio 1
	v_mfma_f32_32x32x16_bf16 v[0:15], v[84:87], v[80:83], v[0:15]
	v_mfma_f32_32x32x16_bf16 v[32:47], v[88:91], v[80:83], v[32:47]
	s_setprio 0
	s_branch .LBB0_1106

.LBB0_1132:
	v_cmp_ge_i32_e64 s[8:9], v183, v201
	v_cmp_lt_i32_e32 vcc, v183, v201
	s_and_saveexec_b64 s[36:37], vcc
	v_add3_u32 v146, v164, s68, -2
	v_cmp_ge_u32_e32 vcc, v146, v205
	v_cmp_lt_u32_e64 s[6:7], v146, v206
	s_and_b64 s[6:7], vcc, s[6:7]
	s_andn2_b64 s[8:9], s[8:9], exec
	s_and_b64 s[6:7], s[6:7], exec
	s_or_b64 s[8:9], s[8:9], s[6:7]
	s_or_b64 exec, exec, s[36:37]
	s_and_saveexec_b64 s[6:7], s[8:9]
	s_cbranch_execz .LBB0_1136
	v_and_b32_e32 v48, 1, v183
	v_cmp_eq_u32_e32 vcc, 1, v48
	s_nop 1
	v_cndmask_b32_e32 v48, 0, v197, vcc
	v_add_u32_e32 v150, v216, v48
	ds_read_b128 v[64:67], v150
	ds_read_b128 v[146:149], v150 offset:4608
	s_waitcnt lgkmcnt(0)
	s_setprio 1
	v_mfma_f32_32x32x16_bf16 v[48:63], v[64:67], v[114:117], v[16:31]
	v_mfma_f32_32x32x16_bf16 v[64:79], v[146:149], v[114:117], v[16:31]
	ds_read_b128 v[146:149], v150 offset:32
	s_waitcnt lgkmcnt(0)
	v_mfma_f32_32x32x16_bf16 v[48:63], v[146:149], v[118:121], v[48:63]
	ds_read_b128 v[146:149], v150 offset:4640
	s_waitcnt lgkmcnt(0)
	v_mfma_f32_32x32x16_bf16 v[64:79], v[146:149], v[118:121], v[64:79]
	ds_read_b128 v[146:149], v150 offset:64
	s_waitcnt lgkmcnt(0)
	v_mfma_f32_32x32x16_bf16 v[48:63], v[146:149], v[122:125], v[48:63]
	ds_read_b128 v[146:149], v150 offset:4672
	s_waitcnt lgkmcnt(0)
	v_mfma_f32_32x32x16_bf16 v[64:79], v[146:149], v[122:125], v[64:79]
	ds_read_b128 v[146:149], v150 offset:96
	s_waitcnt lgkmcnt(0)
	v_mfma_f32_32x32x16_bf16 v[48:63], v[146:149], v[126:129], v[48:63]
	ds_read_b128 v[146:149], v150 offset:4704
	s_waitcnt lgkmcnt(0)
	v_mfma_f32_32x32x16_bf16 v[64:79], v[146:149], v[126:129], v[64:79]
	s_setprio 0

.LBB0_1141:
	s_or_b64 exec, exec, s[2:3]
	s_and_saveexec_b64 s[2:3], s[6:7]
	s_cbranch_execz .LBB0_1122
	v_exp_f32_e32 v146, v96
	v_exp_f32_e32 v96, v80
	v_exp_f32_e32 v147, v97
	v_exp_f32_e32 v97, v81
	v_exp_f32_e32 v148, v98
	v_exp_f32_e32 v98, v82
	v_exp_f32_e32 v149, v99
	v_exp_f32_e32 v99, v83
	v_exp_f32_e32 v150, v100
	v_exp_f32_e32 v100, v84
	v_exp_f32_e32 v151, v101
	v_exp_f32_e32 v101, v85
	v_exp_f32_e32 v152, v102
	v_exp_f32_e32 v102, v86
	v_exp_f32_e32 v153, v103
	v_exp_f32_e32 v103, v87
	v_exp_f32_e32 v104, v104
	v_exp_f32_e32 v80, v88
	v_exp_f32_e32 v105, v105
	v_exp_f32_e32 v81, v89
	v_exp_f32_e32 v88, v106
	v_exp_f32_e32 v82, v90
	v_exp_f32_e32 v89, v107
	v_exp_f32_e32 v83, v91
	v_exp_f32_e32 v90, v108
	v_exp_f32_e32 v84, v92
	v_exp_f32_e32 v91, v109
	v_exp_f32_e32 v85, v93
	v_exp_f32_e32 v110, v110
	v_exp_f32_e32 v86, v94
	v_exp_f32_e32 v111, v111
	v_exp_f32_e32 v87, v95
	v_pk_add_f32 v[158:159], v[148:149], v[98:99]
	v_pk_add_f32 v[160:161], v[146:147], v[96:97]
	v_pk_add_f32 v[154:155], v[152:153], v[102:103]
	v_pk_add_f32 v[156:157], v[150:151], v[100:101]
	v_pk_mov_b32 v[182:183], v[160:161], v[158:159] op_sel:[1,0]
	v_mov_b32_e32 v161, v159
	v_pk_add_f32 v[158:159], v[182:183], v[160:161]
	v_pk_mov_b32 v[160:161], v[156:157], v[154:155] op_sel:[1,0]
	v_mov_b32_e32 v157, v155
	v_pk_add_f32 v[154:155], v[160:161], v[156:157]
	v_pk_add_f32 v[92:93], v[110:111], v[86:87]
	v_pk_add_f32 v[94:95], v[90:91], v[84:85]
	v_pk_add_f32 v[106:107], v[88:89], v[82:83]
	v_pk_add_f32 v[108:109], v[104:105], v[80:81]
	v_pk_add_f32 v[158:159], v[158:159], v[158:159] op_sel_hi:[0,1]
	v_pk_add_f32 v[154:155], v[154:155], v[154:155] op_sel_hi:[0,1]
	v_add_f32_e32 v109, v108, v109
	v_add_f32_e32 v107, v106, v107
	v_mov_b32_e32 v108, v94
	v_mov_b32_e32 v106, v95
	v_mov_b32_e32 v158, v92
	v_mov_b32_e32 v154, v93
	v_pk_add_f32 v[94:95], v[108:109], v[106:107]
	v_pk_add_f32 v[92:93], v[158:159], v[154:155]
	v_cmp_eq_u32_e32 vcc, 1, v181
	v_pk_add_f32 v[92:93], v[94:95], v[92:93]
	v_cvt_pk_bf16_f32 v106, v146, v147
	v_add_f32_e32 v92, v92, v93
	v_cndmask_b32_e32 v93, 0, v228, vcc
	v_add_u32_e32 v93, v217, v93
	v_cvt_pk_bf16_f32 v107, v148, v149
	v_cvt_pk_bf16_f32 v108, v150, v151
	v_cvt_pk_bf16_f32 v109, v152, v153
	ds_read_b64_tr_b16 v[146:147], v93 offset:26624
	ds_read_b64_tr_b16 v[148:149], v93 offset:27776
	ds_read_b64_tr_b16 v[150:151], v93 offset:26688
	ds_read_b64_tr_b16 v[152:153], v93 offset:27840
	s_waitcnt lgkmcnt(0)
	s_setprio 1
	v_mfma_f32_32x32x16_bf16 v[0:15], v[146:149], v[106:109], v[0:15]
	s_setprio 0
	v_cvt_pk_bf16_f32 v104, v104, v105
	v_cvt_pk_bf16_f32 v105, v88, v89
	v_cvt_pk_bf16_f32 v80, v80, v81
	v_cvt_pk_bf16_f32 v81, v82, v83
	v_cvt_pk_bf16_f32 v82, v84, v85
	v_cvt_pk_bf16_f32 v83, v86, v87
	v_add_f32_e32 v143, v143, v92
	s_setprio 1
	v_mfma_f32_32x32x16_bf16 v[32:47], v[150:153], v[106:109], v[32:47]
	s_setprio 0
	v_cvt_pk_bf16_f32 v106, v90, v91
	v_cvt_pk_bf16_f32 v107, v110, v111
	ds_read_b64_tr_b16 v[88:89], v93 offset:28928
	ds_read_b64_tr_b16 v[90:91], v93 offset:30080
	ds_read_b64_tr_b16 v[108:109], v93 offset:28992
	ds_read_b64_tr_b16 v[110:111], v93 offset:30144
	s_waitcnt lgkmcnt(0)
	s_setprio 1
	v_mfma_f32_32x32x16_bf16 v[0:15], v[88:91], v[104:107], v[0:15]
	s_setprio 0
	v_cvt_pk_bf16_f32 v88, v96, v97
	v_cvt_pk_bf16_f32 v89, v98, v99
	v_cvt_pk_bf16_f32 v90, v100, v101
	ds_read_b64_tr_b16 v[94:95], v93 offset:31232
	ds_read_b64_tr_b16 v[96:97], v93 offset:32384
	ds_read_b64_tr_b16 v[98:99], v93 offset:31296
	ds_read_b64_tr_b16 v[100:101], v93 offset:32448
	v_cvt_pk_bf16_f32 v91, v102, v103
	s_setprio 1
	v_mfma_f32_32x32x16_bf16 v[32:47], v[108:111], v[104:107], v[32:47]
	s_waitcnt lgkmcnt(0)
	v_mfma_f32_32x32x16_bf16 v[0:15], v[94:97], v[88:91], v[0:15]
	v_mfma_f32_32x32x16_bf16 v[32:47], v[98:101], v[88:91], v[32:47]
	s_setprio 0
	ds_read_b64_tr_b16 v[84:85], v93 offset:33536
	ds_read_b64_tr_b16 v[86:87], v93 offset:34688
	ds_read_b64_tr_b16 v[88:89], v93 offset:33600
	ds_read_b64_tr_b16 v[90:91], v93 offset:34752
	s_waitcnt lgkmcnt(0)
	s_setprio 1
	v_mfma_f32_32x32x16_bf16 v[0:15], v[84:87], v[80:83], v[0:15]
	v_mfma_f32_32x32x16_bf16 v[32:47], v[88:91], v[80:83], v[32:47]
	s_setprio 0
	s_branch .LBB0_1122

.LBB0_1164:
	s_or_b64 exec, exec, s[2:3]
	v_lshlrev_b64 v[2:3], 6, v[24:25]
	v_lshlrev_b32_e32 v4, 3, v31
	v_lshl_add_u64 v[2:3], v[2:3], 1, v[12:13]
	v_lshlrev_b32_e32 v4, 1, v4
	v_mov_b32_e32 v5, v113
	v_lshl_add_u64 v[2:3], v[2:3], 0, v[4:5]
	v_add_co_u32_e32 v2, vcc, 0x2000, v2
	v_and_b32_e32 v6, 31, v28
	s_nop 0
	v_addc_co_u32_e32 v3, vcc, 0, v3, vcc
	global_load_dwordx4 v[136:139], v[2:3], off
	v_mul_u32_u24_e32 v2, 0xd0, v6
	v_add3_u32 v169, 0, v2, v20
	s_waitcnt lgkmcnt(0)
	s_barrier
	ds_read_b128 v[2:5], v169
	ds_read_b128 v[12:15], v169 offset:32
	s_waitcnt lgkmcnt(0)
	s_setprio 1
	v_mfma_f32_32x32x16_bf16 v[32:47], v[2:5], v[124:127], 0
	s_setprio 0
	ds_read_b128 v[2:5], v169 offset:6656
	ds_read_b128 v[24:27], v169 offset:6688
	v_lshl_add_u64 v[0:1], v[0:1], 0, v[10:11]
	v_and_b32_e32 v6, 63, v28
	v_lshl_add_u64 v[0:1], v[18:19], 1, v[0:1]
	v_lshl_add_u64 v[64:65], s[12:13], 0, v[0:1]
	v_mad_i64_i32 v[0:1], s[2:3], v21, s22, v[10:11]
	s_waitcnt lgkmcnt(0)
	s_setprio 1
	v_mfma_f32_32x32x16_bf16 v[66:81], v[2:5], v[124:127], 0
	s_setprio 0
	v_lshlrev_b32_e32 v165, 2, v29
	v_lshl_add_u64 v[0:1], v[16:17], 1, v[0:1]
	v_lshl_add_u64 v[114:115], s[12:13], 0, v[0:1]
	v_lshl_add_u64 v[0:1], v[8:9], 0, v[22:23]
	v_lshl_add_u64 v[0:1], v[0:1], 0, v[112:113]
	v_mov_b32_e32 v112, 0
	s_mov_b32 s34, 0
	s_setprio 1
	v_mfma_f32_32x32x16_bf16 v[32:47], v[12:15], v[120:123], v[32:47]
	s_setprio 0
	ds_read_b128 v[2:5], v169 offset:64
	ds_read_b128 v[12:15], v169 offset:96
	v_add_u32_e32 v177, -3, v166
	v_lshl_add_u64 v[162:163], s[14:15], 0, v[0:1]
	v_mov_b32_e32 v82, 0xf149f2ca
	s_mov_b64 s[2:3], 0
	v_mov_b32_e32 v0, 0
	v_mov_b32_e32 v1, v112
	s_setprio 1
	v_mfma_f32_32x32x16_bf16 v[66:81], v[24:27], v[120:123], v[66:81]
	s_setprio 0
	ds_read_b128 v[24:27], v169 offset:6720
	ds_read_b128 v[48:51], v169 offset:6752
	ds_read_b128 v[52:55], v169 offset:128
	ds_read_b128 v[56:59], v169 offset:160
	ds_read_b128 v[60:63], v169 offset:6784
	ds_read_b128 v[84:87], v169 offset:6816
	v_mov_b32_e32 v7, v112
	v_mov_b32_e32 v8, v112
	v_mov_b32_e32 v9, v112
	v_mov_b32_e32 v10, v112
	v_mov_b32_e32 v11, v112
	v_mov_b32_e32 v16, 0
	s_waitcnt lgkmcnt(0)
	s_setprio 1
	v_mfma_f32_32x32x16_bf16 v[32:47], v[2:5], v[116:119], v[32:47]
	s_setprio 0
	v_lshlrev_b32_e32 v2, 2, v6
	v_xor_b32_e32 v167, 0x80, v2
	v_lshrrev_b32_e32 v2, 2, v28
	v_and_or_b32 v2, v2, 3, v165
	v_lshlrev_b32_e32 v3, 1, v28
	v_lshlrev_b32_e32 v4, 3, v28
	v_mad_u32_u24 v2, v2, s20, 0
	s_setprio 1
	v_mfma_f32_32x32x16_bf16 v[66:81], v[24:27], v[116:119], v[66:81]
	s_setprio 0
	v_and_b32_e32 v3, 32, v3
	v_and_b32_e32 v4, 24, v4
	v_add3_u32 v168, v2, v3, v4
	v_mov_b32_e32 v2, v112
	v_mov_b32_e32 v3, v112
	v_mov_b32_e32 v4, v112
	v_mov_b32_e32 v5, v112
	s_setprio 1
	v_mfma_f32_32x32x16_bf16 v[32:47], v[12:15], v[106:109], v[32:47]
	s_setprio 0
	v_mov_b32_e32 v6, v112
	v_mov_b32_e32 v12, v112
	v_mov_b32_e32 v13, v112
	v_mov_b32_e32 v14, v112
	v_mov_b32_e32 v15, v112
	v_mov_b32_e32 v17, v112
	v_mov_b32_e32 v18, v112
	s_setprio 1
	v_mfma_f32_32x32x16_bf16 v[66:81], v[48:51], v[106:109], v[66:81]
	s_setprio 0
	v_mov_b32_e32 v19, v112
	v_mov_b32_e32 v20, v112
	v_mov_b32_e32 v21, v112
	v_mov_b32_e32 v22, v112
	v_mov_b32_e32 v23, v112
	v_mov_b32_e32 v24, v112
	v_mov_b32_e32 v25, v112
	s_setprio 1
	v_mfma_f32_32x32x16_bf16 v[32:47], v[52:55], v[102:105], v[32:47]
	s_setprio 0
	v_mov_b32_e32 v26, v112
	v_mov_b32_e32 v27, v112
	v_mov_b32_e32 v28, v112
	v_mov_b32_e32 v29, v112
	v_mov_b32_e32 v30, v112
	v_mov_b32_e32 v31, v112
	s_setprio 1
	v_mfma_f32_32x32x16_bf16 v[66:81], v[60:63], v[102:105], v[66:81]
	s_barrier
	v_mfma_f32_32x32x16_bf16 v[32:47], v[56:59], v[98:101], v[32:47]
	v_mfma_f32_32x32x16_bf16 v[66:81], v[84:87], v[98:101], v[66:81]
	s_setprio 0
	s_branch .LBB0_1166
.LBB0_1165:
	s_or_b64 exec, exec, s[36:37]
	s_add_i32 s34, s34, 1
	s_bitcmp1_b32 s34, 0
	s_cselect_b32 s36, 0x3400, 0
	v_add_u32_e32 v83, s36, v169
	ds_read_b128 v[48:51], v83
	ds_read_b128 v[84:87], v83 offset:32
	v_max_f32_e32 v88, v32, v66
	v_max_f32_e32 v89, v33, v67
	global_load_dwordx4 v[136:139], v[162:163], off
	s_waitcnt lgkmcnt(0)
	s_setprio 1
	v_mfma_f32_32x32x16_bf16 v[48:63], v[48:51], v[124:127], 0
	s_setprio 0
	v_max3_f32 v92, v88, v34, v68
	v_max3_f32 v93, v89, v35, v69
	ds_read_b128 v[88:91], v83 offset:64
	s_and_b64 s[18:19], s[18:19], exec
	s_cselect_b32 s18, 0x2400, 0
	v_cmp_eq_u32_e32 vcc, s34, v177
	v_lshl_add_u64 v[64:65], v[64:65], 0, s[24:25]
	s_setprio 1
	v_mfma_f32_32x32x16_bf16 v[48:63], v[84:87], v[120:123], v[48:63]
	s_setprio 0
	v_max3_f32 v84, v92, v36, v70
	v_max3_f32 v85, v93, v37, v71
	v_lshl_add_u64 v[114:115], v[114:115], 0, s[24:25]
	v_max3_f32 v96, v84, v38, v72
	v_max3_f32 v97, v85, v39, v73
	ds_read_b128 v[84:87], v83 offset:6656
	ds_read_b128 v[146:149], v83 offset:6688
	ds_read_b128 v[92:95], v83 offset:96
	v_max3_f32 v96, v96, v40, v74
	s_waitcnt lgkmcnt(0)
	s_setprio 1
	v_mfma_f32_32x32x16_bf16 v[48:63], v[88:91], v[116:119], v[48:63]
	s_setprio 0
	ds_read_b128 v[150:153], v83 offset:6720
	ds_read_b128 v[154:157], v83 offset:6752
	ds_read_b128 v[88:91], v83 offset:128
	v_max3_f32 v97, v97, v41, v75
	v_max3_f32 v96, v96, v42, v76
	v_lshl_add_u64 v[162:163], v[162:163], 0, s[0:1]
	v_max3_f32 v97, v97, v43, v77
	s_or_b64 s[2:3], vcc, s[2:3]
	s_setprio 1
	v_mfma_f32_32x32x16_bf16 v[48:63], v[92:95], v[106:109], v[48:63]
	s_setprio 0
	v_max3_f32 v92, v96, v44, v78
	v_max3_f32 v93, v97, v45, v79
	s_nop 0
	v_max3_f32 v92, v92, v46, v80
	v_max3_f32 v93, v93, v47, v81
	s_nop 0
	v_max_f32_e32 v96, v92, v93
	ds_read_b128 v[92:95], v83 offset:160
	s_waitcnt lgkmcnt(0)
	s_setprio 1
	v_mfma_f32_32x32x16_bf16 v[48:63], v[88:91], v[102:105], v[48:63]
	s_setprio 0
	ds_bpermute_b32 v97, v167, v96
	ds_read_b128 v[158:161], v83 offset:6784
	ds_read_b128 v[140:143], v83 offset:6816
	s_waitcnt lgkmcnt(0)
	v_max_f32_e32 v83, v96, v97
	s_nop 0
	v_max_f32_e32 v178, v82, v83
	s_nop 0
	v_sub_f32_e32 v179, v82, v178
	s_setprio 1
	v_mfma_f32_32x32x16_bf16 v[48:63], v[92:95], v[98:101], v[48:63]
	s_setprio 0
	v_sub_f32_e32 v32, v32, v178
	v_sub_f32_e32 v33, v33, v178
	v_sub_f32_e32 v41, v41, v178
	v_sub_f32_e32 v40, v40, v178
	v_sub_f32_e32 v39, v39, v178
	v_sub_f32_e32 v38, v38, v178
	v_sub_f32_e32 v37, v37, v178
	s_setprio 1
	v_mfma_f32_32x32x16_bf16 v[82:97], v[84:87], v[124:127], 0
	s_setprio 0
	v_sub_f32_e32 v36, v36, v178
	v_sub_f32_e32 v35, v35, v178
	v_sub_f32_e32 v34, v34, v178
	v_sub_f32_e32 v79, v79, v178
	v_sub_f32_e32 v78, v78, v178
	v_sub_f32_e32 v77, v77, v178
	v_sub_f32_e32 v76, v76, v178
	s_setprio 1
	v_mfma_f32_32x32x16_bf16 v[82:97], v[146:149], v[120:123], v[82:97]
	s_setprio 0
	v_sub_f32_e32 v148, v74, v178
	v_exp_f32_e32 v74, v32
	v_exp_f32_e32 v32, v179
	v_sub_f32_e32 v147, v75, v178
	v_exp_f32_e32 v75, v33
	v_sub_f32_e32 v184, v81, v178
	v_pk_mul_f32 v[14:15], v[14:15], v[32:33] op_sel_hi:[1,0]
	s_setprio 1
	v_mfma_f32_32x32x16_bf16 v[82:97], v[150:153], v[116:119], v[82:97]
	s_setprio 0
	v_mul_f32_e64 v12, v12, v32
	v_mul_f32_e64 v13, v13, v32
	v_mul_f32_e64 v10, v10, v32
	v_mul_f32_e64 v11, v11, v32
	v_mul_f32_e64 v8, v8, v32
	v_mul_f32_e64 v9, v9, v32
	v_pk_mul_f32 v[6:7], v[6:7], v[32:33] op_sel_hi:[1,0]
	v_pk_mul_f32 v[4:5], v[4:5], v[32:33] op_sel_hi:[1,0]
	v_pk_mul_f32 v[2:3], v[2:3], v[32:33] op_sel_hi:[1,0]
	v_pk_mul_f32 v[0:1], v[0:1], v[32:33] op_sel_hi:[1,0]
	s_setprio 1
	v_mfma_f32_32x32x16_bf16 v[82:97], v[154:157], v[106:109], v[82:97]
	s_setprio 0
	v_mul_f32_e64 v30, v30, v32
	v_mul_f32_e64 v31, v31, v32
	v_add_u32_e32 v33, s18, v168
	v_sub_f32_e32 v146, v80, v178
	v_exp_f32_e32 v80, v34
	v_exp_f32_e32 v81, v35
	v_exp_f32_e32 v154, v36
	v_exp_f32_e32 v155, v37
	s_setprio 1
	v_mfma_f32_32x32x16_bf16 v[82:97], v[158:161], v[102:105], v[82:97]
	s_setprio 0
	v_exp_f32_e32 v156, v38
	v_exp_f32_e32 v157, v39
	v_exp_f32_e32 v158, v40
	v_exp_f32_e32 v159, v41
	v_exp_f32_e32 v38, v76
	v_exp_f32_e32 v40, v78
	v_exp_f32_e32 v41, v79
	v_exp_f32_e32 v39, v77
	ds_read_b64_tr_b16 v[76:77], v33 offset:26624
	ds_read_b64_tr_b16 v[78:79], v33 offset:27776
	ds_read_b64_tr_b16 v[152:153], v33 offset:27840
	ds_read_b64_tr_b16 v[150:151], v33 offset:26688
	v_sub_f32_e32 v44, v44, v178
	v_exp_f32_e32 v36, v148
	v_exp_f32_e32 v37, v147
	v_exp_f32_e32 v180, v44
	v_exp_f32_e32 v44, v146
	v_pk_mul_f32 v[28:29], v[28:29], v[32:33] op_sel_hi:[1,0]
	v_pk_mul_f32 v[26:27], v[26:27], v[32:33] op_sel_hi:[1,0]
	v_cvt_pk_bf16_f32 v146, v74, v75
	v_cvt_pk_bf16_f32 v147, v80, v81
	v_cvt_pk_bf16_f32 v148, v154, v155
	v_cvt_pk_bf16_f32 v149, v156, v157
	v_pk_mul_f32 v[24:25], v[24:25], v[32:33] op_sel_hi:[1,0]
	v_pk_mul_f32 v[22:23], v[22:23], v[32:33] op_sel_hi:[1,0]
	v_pk_mul_f32 v[20:21], v[20:21], v[32:33] op_sel_hi:[1,0]
	v_pk_mul_f32 v[18:19], v[18:19], v[32:33] op_sel_hi:[1,0]
	v_pk_mul_f32 v[16:17], v[16:17], v[32:33] op_sel_hi:[1,0]
	s_waitcnt lgkmcnt(0)
	s_setprio 1
	v_mfma_f32_32x32x16_bf16 v[0:15], v[76:79], v[146:149], v[0:15]
	s_setprio 0
	v_sub_f32_e32 v47, v47, v178
	v_sub_f32_e32 v46, v46, v178
	v_sub_f32_e32 v45, v45, v178
	v_sub_f32_e32 v43, v43, v178
	v_sub_f32_e32 v42, v42, v178
	v_exp_f32_e32 v160, v42
	v_exp_f32_e32 v161, v43
	s_setprio 1
	v_mfma_f32_32x32x16_bf16 v[16:31], v[150:153], v[146:149], v[16:31]
	s_setprio 0
	v_exp_f32_e32 v181, v45
	v_exp_f32_e32 v182, v46
	v_exp_f32_e32 v183, v47
	ds_read_b64_tr_b16 v[76:77], v33 offset:28928
	ds_read_b64_tr_b16 v[78:79], v33 offset:30080
	ds_read_b64_tr_b16 v[152:153], v33 offset:30144
	ds_read_b64_tr_b16 v[150:151], v33 offset:28992
	v_sub_f32_e32 v73, v73, v178
	v_sub_f32_e32 v72, v72, v178
	v_sub_f32_e32 v71, v71, v178
	v_sub_f32_e32 v70, v70, v178
	v_sub_f32_e32 v69, v69, v178
	v_sub_f32_e32 v68, v68, v178
	v_sub_f32_e32 v67, v67, v178
	v_sub_f32_e32 v66, v66, v178
	v_exp_f32_e32 v66, v66
	v_exp_f32_e32 v67, v67
	v_exp_f32_e32 v68, v68
	v_exp_f32_e32 v69, v69
	v_exp_f32_e32 v70, v70
	v_exp_f32_e32 v71, v71
	v_exp_f32_e32 v72, v72
	v_exp_f32_e32 v73, v73
	v_cvt_pk_bf16_f32 v146, v158, v159
	v_cvt_pk_bf16_f32 v147, v160, v161
	v_cvt_pk_bf16_f32 v148, v180, v181
	v_cvt_pk_bf16_f32 v149, v182, v183
	v_pk_add_f32 v[154:155], v[154:155], v[70:71]
	v_pk_add_f32 v[80:81], v[80:81], v[68:69]
	s_waitcnt lgkmcnt(0)
	s_setprio 1
	v_mfma_f32_32x32x16_bf16 v[0:15], v[76:79], v[146:149], v[0:15]
	s_setprio 0
	v_add_f32_e64 v78, v156, v72
	v_add_f32_e64 v79, v157, v73
	v_add_f32_e64 v156, v74, v66
	v_add_f32_e64 v157, v75, v67
	ds_read_b64_tr_b16 v[74:75], v33 offset:31232
	ds_read_b64_tr_b16 v[76:77], v33 offset:32384
	v_cvt_pk_bf16_f32 v66, v66, v67
	v_cvt_pk_bf16_f32 v67, v68, v69
	v_cvt_pk_bf16_f32 v68, v70, v71
	v_cvt_pk_bf16_f32 v69, v72, v73
	s_setprio 1
	v_mfma_f32_32x32x16_bf16 v[16:31], v[150:153], v[146:149], v[16:31]
	s_setprio 0
	ds_read_b64_tr_b16 v[72:73], v33 offset:32448
	ds_read_b64_tr_b16 v[70:71], v33 offset:31296
	v_exp_f32_e32 v45, v184
	v_pk_add_f32 v[184:185], v[158:159], v[36:37]
	v_pk_mov_b32 v[158:159], v[156:157], v[80:81] op_sel:[1,0]
	v_mov_b32_e32 v157, v81
	v_pk_add_f32 v[34:35], v[182:183], v[44:45]
	v_pk_add_f32 v[42:43], v[180:181], v[40:41]
	s_waitcnt lgkmcnt(0)
	s_setprio 1
	v_mfma_f32_32x32x16_bf16 v[0:15], v[74:77], v[66:69], v[0:15]
	s_setprio 0
	v_add_f32_e64 v74, v158, v156
	v_add_f32_e64 v75, v159, v157
	v_add_f32_e64 v46, v160, v38
	v_add_f32_e64 v47, v161, v39
	v_add_f32_e64 v80, v74, v74
	v_add_f32_e64 v81, v74, v75
	v_pk_mov_b32 v[74:75], v[154:155], v[78:79] op_sel:[1,0]
	v_mov_b32_e32 v155, v79
	v_pk_add_f32 v[78:79], v[74:75], v[154:155]
	ds_read_b64_tr_b16 v[74:75], v33 offset:33536
	ds_read_b64_tr_b16 v[76:77], v33 offset:34688
	s_setprio 1
	v_mfma_f32_32x32x16_bf16 v[16:31], v[70:73], v[66:69], v[16:31]
	s_setprio 0
	ds_read_b64_tr_b16 v[68:69], v33 offset:34752
	ds_read_b64_tr_b16 v[66:67], v33 offset:33600
	v_add_f32_e64 v70, v78, v78
	v_add_f32_e64 v71, v78, v79
	v_cvt_pk_bf16_f32 v36, v36, v37
	v_cvt_pk_bf16_f32 v37, v38, v39
	v_cvt_pk_bf16_f32 v38, v40, v41
	v_cvt_pk_bf16_f32 v39, v44, v45
	v_add_f32_e32 v41, v184, v185
	v_add_f32_e32 v45, v46, v47
	v_mov_b32_e32 v40, v42
	v_mov_b32_e32 v44, v43
	v_mov_b32_e32 v80, v34
	v_mov_b32_e32 v70, v35
	v_pk_add_f32 v[40:41], v[40:41], v[44:45]
	v_pk_add_f32 v[34:35], v[80:81], v[70:71]
	s_waitcnt lgkmcnt(0)
	s_setprio 1
	v_mfma_f32_32x32x16_bf16 v[0:15], v[74:77], v[36:39], v[0:15]
	s_setprio 0
	v_add_f32_e64 v34, v40, v34
	v_add_f32_e64 v35, v41, v35
	v_add_f32_e32 v33, v34, v35
	ds_bpermute_b32 v34, v167, v33
	s_barrier
	s_waitcnt lgkmcnt(0)
	s_setprio 1
	v_mfma_f32_32x32x16_bf16 v[16:31], v[66:69], v[36:39], v[16:31]
	s_setprio 0
	v_mov_b64_e32 v[66:67], v[82:83]
	v_mov_b64_e32 v[68:69], v[84:85]
	v_mov_b64_e32 v[70:71], v[86:87]
	v_mov_b64_e32 v[72:73], v[88:89]
	v_mov_b64_e32 v[74:75], v[90:91]
	v_mov_b64_e32 v[76:77], v[92:93]
	v_mov_b64_e32 v[78:79], v[94:95]
	v_mov_b64_e32 v[80:81], v[96:97]
	v_mov_b32_e32 v82, v178
	s_nop 0
	s_setprio 1
	v_mfma_f32_32x32x16_bf16 v[66:81], v[140:143], v[98:101], v[66:81]
	s_setprio 0
	v_add_f32_e32 v140, v33, v34
	v_fmac_f32_e32 v140, v112, v32
	v_mov_b64_e32 v[32:33], v[48:49]
	v_mov_b32_e32 v112, v140
	v_mov_b64_e32 v[34:35], v[50:51]
	v_mov_b64_e32 v[36:37], v[52:53]
	v_mov_b64_e32 v[38:39], v[54:55]
	v_mov_b64_e32 v[40:41], v[56:57]
	v_mov_b64_e32 v[42:43], v[58:59]
	v_mov_b64_e32 v[44:45], v[60:61]
	v_mov_b64_e32 v[46:47], v[62:63]
	s_andn2_b64 exec, exec, s[2:3]
	s_cbranch_execz .LBB0_1170

.LBB0_1170:
	s_or_b64 exec, exec, s[2:3]
	s_waitcnt vmcnt(0)
	ds_write_b128 v173, v[132:135] offset:13312
	s_and_saveexec_b64 s[2:3], s[6:7]
	ds_write_b128 v171, v[128:131] offset:13312
	s_or_b64 exec, exec, s[2:3]
	ds_write_b128 v170, v[136:139] offset:26624
	ds_read_b128 v[32:35], v169
	ds_read_b128 v[82:85], v169 offset:32
	ds_read_b128 v[86:89], v169 offset:6656
	ds_read_b128 v[90:93], v169 offset:6688
	ds_read_b128 v[94:97], v169 offset:64
	ds_read_b128 v[128:131], v169 offset:96
	ds_read_b128 v[132:135], v169 offset:128
	v_max_f32_e32 v64, v48, v66
	v_max_f32_e32 v65, v49, v67
	s_waitcnt lgkmcnt(6)
	s_setprio 1
	v_mfma_f32_32x32x16_bf16 v[32:47], v[32:35], v[124:127], 0
	s_setprio 0
	v_max3_f32 v64, v64, v50, v68
	v_max3_f32 v65, v65, v51, v69
	s_nop 0
	v_max3_f32 v64, v64, v52, v70
	v_max3_f32 v65, v65, v53, v71
	s_nop 0
	v_max3_f32 v64, v64, v54, v72
	s_waitcnt lgkmcnt(5)
	s_setprio 1
	v_mfma_f32_32x32x16_bf16 v[32:47], v[82:85], v[120:123], v[32:47]
	s_setprio 0
	v_max3_f32 v65, v65, v55, v73
	v_max3_f32 v64, v64, v56, v74
	s_nop 0
	v_max3_f32 v65, v65, v57, v75
	v_max3_f32 v64, v64, v58, v76
	s_nop 0
	v_max3_f32 v65, v65, v59, v77
	s_waitcnt lgkmcnt(2)
	s_setprio 1
	v_mfma_f32_32x32x16_bf16 v[32:47], v[94:97], v[116:119], v[32:47]
	s_setprio 0
	v_max3_f32 v64, v64, v60, v78
	v_max3_f32 v65, v65, v61, v79
	s_nop 0
	v_max3_f32 v64, v64, v62, v80
	v_max3_f32 v65, v65, v63, v81
	s_nop 0
	v_max_f32_e32 v64, v64, v65
	s_waitcnt lgkmcnt(1)
	s_setprio 1
	v_mfma_f32_32x32x16_bf16 v[32:47], v[128:131], v[106:109], v[32:47]
	s_setprio 0
	ds_read_b128 v[94:97], v169 offset:6720
	ds_read_b128 v[128:131], v169 offset:6752
	ds_read_b128 v[146:149], v169 offset:160
	ds_read_b128 v[82:85], v169 offset:6784
	ds_bpermute_b32 v65, v167, v64
	s_waitcnt lgkmcnt(0)
	v_max_f32_e32 v64, v64, v65
	s_nop 0
	v_max_f32_e32 v136, v178, v64
	s_nop 0
	v_sub_f32_e32 v137, v63, v136
	s_setprio 1
	v_mfma_f32_32x32x16_bf16 v[32:47], v[132:135], v[102:105], v[32:47]
	s_setprio 0
	v_sub_f32_e32 v141, v62, v136
	v_sub_f32_e32 v151, v61, v136
	v_sub_f32_e32 v152, v60, v136
	v_sub_f32_e32 v143, v59, v136
	v_sub_f32_e32 v142, v58, v136
	v_sub_f32_e32 v139, v57, v136
	v_sub_f32_e32 v138, v56, v136
	s_setprio 1
	v_mfma_f32_32x32x16_bf16 v[32:47], v[146:149], v[98:101], v[32:47]
	s_setprio 0
	v_sub_f32_e32 v135, v55, v136
	v_sub_f32_e32 v134, v54, v136
	v_sub_f32_e32 v133, v53, v136
	v_sub_f32_e32 v132, v52, v136
	v_sub_f32_e32 v146, v51, v136
	v_sub_f32_e32 v147, v50, v136
	v_sub_f32_e32 v112, v178, v136
	s_setprio 1
	v_mfma_f32_32x32x16_bf16 v[50:65], v[86:89], v[124:127], 0
	s_setprio 0
	v_exp_f32_e32 v150, v112
	v_sub_f32_e32 v49, v49, v136
	v_sub_f32_e32 v48, v48, v136
	v_exp_f32_e32 v48, v48
	v_exp_f32_e32 v49, v49
	v_exp_f32_e32 v132, v132
	v_exp_f32_e32 v133, v133
	s_setprio 1
	v_mfma_f32_32x32x16_bf16 v[50:65], v[90:93], v[120:123], v[50:65]
	s_setprio 0
	v_exp_f32_e32 v134, v134
	v_exp_f32_e32 v135, v135
	v_pk_mul_f32 v[92:93], v[10:11], v[150:151] op_sel_hi:[1,0]
	v_pk_mul_f32 v[90:91], v[8:9], v[150:151] op_sel_hi:[1,0]
	v_pk_mul_f32 v[88:89], v[6:7], v[150:151] op_sel_hi:[1,0]
	v_pk_mul_f32 v[86:87], v[4:5], v[150:151] op_sel_hi:[1,0]
	v_cvt_pk_bf16_f32 v4, v48, v49
	s_setprio 1
	v_mfma_f32_32x32x16_bf16 v[50:65], v[94:97], v[116:119], v[50:65]
	s_setprio 0
	v_mul_f32_e64 v96, v14, v150
	v_mul_f32_e64 v97, v15, v150
	v_mul_f32_e64 v94, v12, v150
	v_mul_f32_e64 v95, v13, v150
	v_cvt_pk_bf16_f32 v6, v132, v133
	v_cvt_pk_bf16_f32 v7, v134, v135
	v_exp_f32_e32 v138, v138
	v_exp_f32_e32 v139, v139
	v_exp_f32_e32 v142, v142
	s_setprio 1
	v_mfma_f32_32x32x16_bf16 v[50:65], v[128:131], v[106:109], v[50:65]
	s_setprio 0
	v_exp_f32_e32 v128, v147
	v_exp_f32_e32 v129, v146
	ds_read_b128 v[146:149], v169 offset:6816
	v_exp_f32_e32 v143, v143
	v_exp_f32_e32 v152, v152
	v_cvt_pk_bf16_f32 v5, v128, v129
	v_exp_f32_e32 v153, v151
	s_setprio 1
	v_mfma_f32_32x32x16_bf16 v[50:65], v[82:85], v[102:105], v[50:65]
	s_setprio 0
	v_mul_f32_e64 v84, v2, v150
	v_mul_f32_e64 v85, v3, v150
	v_mul_f32_e64 v82, v0, v150
	v_mul_f32_e64 v83, v1, v150
	ds_read_b64_tr_b16 v[0:1], v168 offset:35840
	ds_read_b64_tr_b16 v[2:3], v168 offset:36992
	ds_read_b64_tr_b16 v[10:11], v168 offset:37056
	ds_read_b64_tr_b16 v[8:9], v168 offset:35904
	v_exp_f32_e32 v154, v141
	v_exp_f32_e32 v155, v137
	v_sub_f32_e32 v68, v68, v136
	s_waitcnt lgkmcnt(2)
	s_setprio 1
	v_mfma_f32_32x32x16_bf16 v[82:97], v[0:3], v[4:7], v[82:97]
	s_setprio 0
	ds_read_b64_tr_b16 v[0:1], v168 offset:38144
	ds_read_b64_tr_b16 v[2:3], v168 offset:39296
	v_sub_f32_e32 v67, v67, v136
	v_sub_f32_e32 v66, v66, v136
	v_sub_f32_e32 v159, v81, v136
	v_sub_f32_e32 v158, v80, v136
	v_sub_f32_e32 v157, v79, v136
	v_sub_f32_e32 v156, v78, v136
	v_sub_f32_e32 v160, v77, v136
	v_sub_f32_e32 v161, v76, v136
	v_sub_f32_e32 v162, v75, v136
	v_sub_f32_e32 v163, v74, v136
	v_sub_f32_e32 v171, v73, v136
	v_sub_f32_e32 v172, v72, v136
	v_sub_f32_e32 v173, v71, v136
	v_sub_f32_e32 v174, v70, v136
	v_sub_f32_e32 v175, v69, v136
	v_exp_f32_e32 v114, v66
	v_exp_f32_e32 v115, v67
	v_exp_f32_e32 v130, v68
	v_pk_mul_f32 v[80:81], v[30:31], v[150:151] op_sel_hi:[1,0]
	v_pk_mul_f32 v[78:79], v[28:29], v[150:151] op_sel_hi:[1,0]
	v_pk_mul_f32 v[76:77], v[26:27], v[150:151] op_sel_hi:[1,0]
	v_pk_mul_f32 v[74:75], v[24:25], v[150:151] op_sel_hi:[1,0]
	v_pk_mul_f32 v[72:73], v[22:23], v[150:151] op_sel_hi:[1,0]
	v_pk_mul_f32 v[70:71], v[20:21], v[150:151] op_sel_hi:[1,0]
	v_pk_mul_f32 v[68:69], v[18:19], v[150:151] op_sel_hi:[1,0]
	v_pk_mul_f32 v[66:67], v[16:17], v[150:151] op_sel_hi:[1,0]
	v_exp_f32_e32 v131, v175
	v_exp_f32_e32 v24, v174
	s_waitcnt lgkmcnt(2)
	s_setprio 1
	v_mfma_f32_32x32x16_bf16 v[66:81], v[8:11], v[4:7], v[66:81]
	s_setprio 0
	v_cvt_pk_bf16_f32 v4, v138, v139
	v_cvt_pk_bf16_f32 v5, v142, v143
	v_cvt_pk_bf16_f32 v6, v152, v153
	v_cvt_pk_bf16_f32 v7, v154, v155
	ds_read_b64_tr_b16 v[10:11], v168 offset:39360
	ds_read_b64_tr_b16 v[8:9], v168 offset:38208
	v_exp_f32_e32 v25, v173
	v_exp_f32_e32 v26, v172
	s_waitcnt lgkmcnt(2)
	s_setprio 1
	v_mfma_f32_32x32x16_bf16 v[82:97], v[0:3], v[4:7], v[82:97]
	s_setprio 0
	v_exp_f32_e32 v27, v171
	ds_read_b64_tr_b16 v[0:1], v168 offset:40448
	ds_read_b64_tr_b16 v[2:3], v168 offset:41600
	v_exp_f32_e32 v28, v163
	v_exp_f32_e32 v29, v162
	v_exp_f32_e32 v30, v161
	v_exp_f32_e32 v31, v160
	v_exp_f32_e32 v156, v156
	s_waitcnt lgkmcnt(2)
	s_setprio 1
	v_mfma_f32_32x32x16_bf16 v[66:81], v[8:11], v[4:7], v[66:81]
	s_setprio 0
	v_cvt_pk_bf16_f32 v4, v114, v115
	v_cvt_pk_bf16_f32 v5, v130, v131
	v_cvt_pk_bf16_f32 v6, v24, v25
	v_cvt_pk_bf16_f32 v7, v26, v27
	ds_read_b64_tr_b16 v[10:11], v168 offset:41664
	ds_read_b64_tr_b16 v[8:9], v168 offset:40512
	v_exp_f32_e32 v157, v157
	v_exp_f32_e32 v158, v158
	s_waitcnt lgkmcnt(2)
	s_setprio 1
	v_mfma_f32_32x32x16_bf16 v[82:97], v[0:3], v[4:7], v[82:97]
	s_setprio 0
	ds_read_b64_tr_b16 v[0:1], v168 offset:42752
	ds_read_b64_tr_b16 v[2:3], v168 offset:43904
	v_exp_f32_e32 v159, v159
	v_lshlrev_b32_e32 v112, 13, v166
	v_pk_add_f32 v[26:27], v[134:135], v[26:27]
	v_pk_add_f32 v[24:25], v[132:133], v[24:25]
	s_waitcnt lgkmcnt(2)
	s_setprio 1
	v_mfma_f32_32x32x16_bf16 v[66:81], v[8:11], v[4:7], v[66:81]
	s_setprio 0
	v_cvt_pk_bf16_f32 v4, v28, v29
	v_cvt_pk_bf16_f32 v5, v30, v31
	v_cvt_pk_bf16_f32 v6, v156, v157
	v_cvt_pk_bf16_f32 v7, v158, v159
	ds_read_b64_tr_b16 v[10:11], v168 offset:43968
	ds_read_b64_tr_b16 v[8:9], v168 offset:42816
	v_pk_add_f32 v[30:31], v[142:143], v[30:31]
	v_pk_add_f32 v[28:29], v[138:139], v[28:29]
	s_waitcnt lgkmcnt(2)
	s_setprio 1
	v_mfma_f32_32x32x16_bf16 v[82:97], v[0:3], v[4:7], v[82:97]
	s_setprio 0
	v_lshl_add_u64 v[0:1], v[110:111], 0, v[112:113]
	v_add_co_u32_e32 v0, vcc, 0xffffe000, v0
	v_add_f32_e64 v110, v154, v158
	v_add_f32_e64 v111, v155, v159
	v_addc_co_u32_e32 v1, vcc, -1, v1, vcc
	global_load_dwordx4 v[0:3], v[0:1], off
	s_waitcnt lgkmcnt(0)
	s_barrier
	s_setprio 1
	v_mfma_f32_32x32x16_bf16 v[66:81], v[8:11], v[4:7], v[66:81]
	s_setprio 0
	s_waitcnt vmcnt(0)
	ds_write_b128 v170, v[0:3] offset:35840
	ds_read_b128 v[0:3], v169 offset:13312
	ds_read_b128 v[16:19], v169 offset:13344
	s_waitcnt lgkmcnt(1)
	s_setprio 1
	v_mfma_f32_32x32x16_bf16 v[0:15], v[0:3], v[124:127], 0
	s_waitcnt lgkmcnt(0)
	v_mfma_f32_32x32x16_bf16 v[0:15], v[16:19], v[120:123], v[0:15]
	ds_read_b128 v[16:19], v169 offset:13376
	ds_read_b128 v[20:23], v169 offset:13408
	s_waitcnt lgkmcnt(1)
	v_mfma_f32_32x32x16_bf16 v[0:15], v[16:19], v[116:119], v[0:15]
	ds_read_b128 v[16:19], v169 offset:13440
	s_waitcnt lgkmcnt(1)
	v_mfma_f32_32x32x16_bf16 v[0:15], v[20:23], v[106:109], v[0:15]
	s_setprio 0
	v_add_f32_e64 v20, v128, v130
	v_add_f32_e64 v21, v129, v131
	v_add_f32_e64 v22, v48, v114
	v_add_f32_e64 v23, v49, v115
	ds_read_b128 v[128:131], v169 offset:20000
	v_pk_mov_b32 v[48:49], v[22:23], v[20:21] op_sel:[1,0]
	v_mov_b32_e32 v23, v21
	v_pk_add_f32 v[48:49], v[48:49], v[22:23]
	ds_read_b128 v[20:23], v169 offset:13472
	s_waitcnt lgkmcnt(2)
	s_setprio 1
	v_mfma_f32_32x32x16_bf16 v[0:15], v[16:19], v[102:105], v[0:15]
	s_setprio 0
	v_pk_mov_b32 v[16:17], v[24:25], v[26:27] op_sel:[1,0]
	v_mov_b32_e32 v25, v27
	v_pk_add_f32 v[16:17], v[16:17], v[24:25]
	v_add_f32_e32 v25, v28, v29
	v_pk_add_f32 v[114:115], v[16:17], v[16:17] op_sel_hi:[0,1]
	ds_read_b128 v[16:19], v169 offset:19968
	v_pk_add_f32 v[48:49], v[48:49], v[48:49] op_sel_hi:[0,1]
	s_setprio 1
	v_mfma_f32_32x32x16_bf16 v[50:65], v[146:149], v[98:101], v[50:65]
	s_setprio 0
	v_add_f32_e64 v146, v152, v156
	v_add_f32_e64 v147, v153, v157
	v_mov_b32_e32 v48, v110
	v_mov_b32_e32 v24, v146
	v_mov_b32_e32 v114, v111
	v_pk_add_f32 v[48:49], v[48:49], v[114:115]
	v_max_f32_e32 v111, v33, v51
	v_max_f32_e32 v110, v32, v50
	s_waitcnt lgkmcnt(1)
	s_setprio 1
	v_mfma_f32_32x32x16_bf16 v[0:15], v[20:23], v[98:101], v[0:15]
	s_setprio 0
	v_add_f32_e32 v21, v30, v31
	v_mov_b32_e32 v20, v147
	v_add_f32_e64 v132, v24, v20
	v_add_f32_e64 v133, v25, v21
	v_max3_f32 v111, v111, v35, v53
	v_max3_f32 v110, v110, v34, v52
	v_add_f32_e64 v48, v132, v48
	v_add_f32_e64 v49, v133, v49
	s_waitcnt lgkmcnt(0)
	s_setprio 1
	v_mfma_f32_32x32x16_bf16 v[16:31], v[16:19], v[124:127], 0
	s_setprio 0
	ds_read_b128 v[124:127], v169 offset:20032
	ds_read_b128 v[132:135], v169 offset:20064
	ds_read_b128 v[146:149], v169 offset:20096
	v_add_f32_e32 v48, v48, v49
	ds_bpermute_b32 v49, v167, v48
	v_max3_f32 v111, v111, v37, v55
	v_max3_f32 v110, v110, v36, v54
	s_waitcnt lgkmcnt(0)
	v_add_f32_e32 v114, v48, v49
	s_setprio 1
	v_mfma_f32_32x32x16_bf16 v[16:31], v[128:131], v[120:123], v[16:31]
	s_setprio 0
	v_max3_f32 v111, v111, v39, v57
	v_max3_f32 v110, v110, v38, v56
	s_nop 0
	v_max3_f32 v111, v111, v41, v59
	v_max3_f32 v110, v110, v40, v58
	s_nop 0
	v_max3_f32 v111, v111, v43, v61
	s_setprio 1
	v_mfma_f32_32x32x16_bf16 v[16:31], v[124:127], v[116:119], v[16:31]
	s_setprio 0
	v_max3_f32 v110, v110, v42, v60
	v_max3_f32 v111, v111, v45, v63
	s_nop 0
	v_max3_f32 v110, v110, v44, v62
	s_setprio 1
	v_mfma_f32_32x32x16_bf16 v[16:31], v[132:135], v[106:109], v[16:31]
	s_setprio 0
	v_max3_f32 v106, v110, v46, v64
	v_max3_f32 v107, v111, v47, v65
	v_mul_f32_e32 v110, v140, v150
	v_max_f32_e32 v111, v106, v107
	ds_bpermute_b32 v112, v167, v111
	s_waitcnt lgkmcnt(0)
	v_max_f32_e32 v48, v111, v112
	ds_read_b128 v[106:109], v169 offset:20128
	v_max_f32_e32 v111, v136, v48
	s_setprio 1
	v_mfma_f32_32x32x16_bf16 v[16:31], v[146:149], v[102:105], v[16:31]
	s_setprio 0
	v_sub_f32_e32 v48, v136, v111
	v_sub_f32_e32 v39, v39, v111
	v_sub_f32_e32 v38, v38, v111
	v_sub_f32_e32 v37, v37, v111
	v_sub_f32_e32 v36, v36, v111
	v_sub_f32_e32 v35, v35, v111
	v_sub_f32_e32 v34, v34, v111
	v_sub_f32_e32 v33, v33, v111
	v_sub_f32_e32 v32, v32, v111
	v_sub_f32_e32 v64, v64, v111
	v_exp_f32_e32 v132, v32
	v_exp_f32_e32 v133, v33
	v_exp_f32_e32 v134, v34
	v_exp_f32_e32 v135, v35
	v_exp_f32_e32 v136, v36
	v_exp_f32_e32 v137, v37
	v_exp_f32_e32 v140, v38
	v_exp_f32_e32 v141, v39
	v_exp_f32_e32 v122, v64
	v_exp_f32_e32 v64, v48
	ds_read_b64_tr_b16 v[32:33], v168 offset:26624
	ds_read_b64_tr_b16 v[34:35], v168 offset:27776
	v_sub_f32_e32 v45, v45, v111
	v_sub_f32_e32 v44, v44, v111
	v_sub_f32_e32 v43, v43, v111
	v_sub_f32_e32 v42, v42, v111
	v_sub_f32_e32 v49, v65, v111
	v_sub_f32_e32 v63, v63, v111
	v_sub_f32_e32 v62, v62, v111
	v_sub_f32_e32 v61, v61, v111
	v_sub_f32_e32 v60, v60, v111
	v_sub_f32_e32 v59, v59, v111
	v_sub_f32_e32 v58, v58, v111
	v_sub_f32_e32 v57, v57, v111
	v_sub_f32_e32 v56, v56, v111
	v_sub_f32_e32 v55, v55, v111
	v_sub_f32_e32 v54, v54, v111
	v_sub_f32_e32 v53, v53, v111
	v_sub_f32_e32 v52, v52, v111
	v_sub_f32_e32 v51, v51, v111
	v_sub_f32_e32 v50, v50, v111
	v_exp_f32_e32 v128, v50
	v_exp_f32_e32 v129, v51
	v_exp_f32_e32 v130, v52
	v_exp_f32_e32 v131, v53
	v_exp_f32_e32 v138, v54
	v_exp_f32_e32 v139, v55
	v_exp_f32_e32 v142, v56
	v_exp_f32_e32 v143, v57
	v_exp_f32_e32 v104, v58
	v_exp_f32_e32 v105, v59
	v_exp_f32_e32 v148, v42
	v_exp_f32_e32 v116, v60
	v_exp_f32_e32 v149, v43
	v_exp_f32_e32 v150, v44
	v_exp_f32_e32 v120, v62
	v_exp_f32_e32 v151, v45
	v_exp_f32_e32 v123, v49
	v_exp_f32_e32 v121, v63
	v_exp_f32_e32 v117, v61
	v_pk_mul_f32 v[62:63], v[96:97], v[64:65] op_sel_hi:[1,0]
	v_pk_mul_f32 v[60:61], v[94:95], v[64:65] op_sel_hi:[1,0]
	v_pk_mul_f32 v[58:59], v[92:93], v[64:65] op_sel_hi:[1,0]
	v_pk_mul_f32 v[56:57], v[90:91], v[64:65] op_sel_hi:[1,0]
	v_pk_mul_f32 v[54:55], v[88:89], v[64:65] op_sel_hi:[1,0]
	v_pk_mul_f32 v[52:53], v[86:87], v[64:65] op_sel_hi:[1,0]
	v_pk_mul_f32 v[50:51], v[84:85], v[64:65] op_sel_hi:[1,0]
	v_pk_mul_f32 v[48:49], v[82:83], v[64:65] op_sel_hi:[1,0]
	v_pk_mul_f32 v[44:45], v[78:79], v[64:65] op_sel_hi:[1,0]
	v_pk_mul_f32 v[42:43], v[76:77], v[64:65] op_sel_hi:[1,0]
	v_cvt_pk_bf16_f32 v76, v132, v133
	v_cvt_pk_bf16_f32 v77, v134, v135
	v_cvt_pk_bf16_f32 v78, v136, v137
	v_cvt_pk_bf16_f32 v79, v140, v141
	v_sub_f32_e32 v47, v47, v111
	v_sub_f32_e32 v46, v46, v111
	s_waitcnt lgkmcnt(0)
	s_setprio 1
	v_mfma_f32_32x32x16_bf16 v[48:63], v[32:35], v[76:79], v[48:63]
	s_setprio 0
	v_sub_f32_e32 v41, v41, v111
	v_sub_f32_e32 v40, v40, v111
	v_exp_f32_e32 v152, v46
	v_exp_f32_e32 v153, v47
	v_pk_mul_f32 v[46:47], v[80:81], v[64:65] op_sel_hi:[1,0]
	ds_read_b64_tr_b16 v[82:83], v168 offset:27840
	ds_read_b64_tr_b16 v[80:81], v168 offset:26688
	v_exp_f32_e32 v146, v40
	v_exp_f32_e32 v147, v41
	v_pk_mul_f32 v[34:35], v[68:69], v[64:65] op_sel_hi:[1,0]
	v_pk_mul_f32 v[32:33], v[66:67], v[64:65] op_sel_hi:[1,0]
	ds_read_b64_tr_b16 v[66:67], v168 offset:28928
	ds_read_b64_tr_b16 v[68:69], v168 offset:30080
	v_pk_mul_f32 v[40:41], v[74:75], v[64:65] op_sel_hi:[1,0]
	v_pk_mul_f32 v[38:39], v[72:73], v[64:65] op_sel_hi:[1,0]
	v_pk_mul_f32 v[36:37], v[70:71], v[64:65] op_sel_hi:[1,0]
	v_cvt_pk_bf16_f32 v70, v146, v147
	v_cvt_pk_bf16_f32 v71, v148, v149
	s_waitcnt lgkmcnt(2)
	s_setprio 1
	v_mfma_f32_32x32x16_bf16 v[32:47], v[80:83], v[76:79], v[32:47]
	s_setprio 0
	v_cvt_pk_bf16_f32 v72, v150, v151
	v_cvt_pk_bf16_f32 v73, v152, v153
	ds_read_b64_tr_b16 v[76:77], v168 offset:30144
	ds_read_b64_tr_b16 v[74:75], v168 offset:28992
	v_add_f32_e64 v78, v134, v130
	v_add_f32_e64 v79, v135, v131
	v_pk_add_f32 v[80:81], v[140:141], v[142:143]
	v_pk_add_f32 v[82:83], v[132:133], v[128:129]
	v_pk_add_f32 v[84:85], v[136:137], v[138:139]
	s_waitcnt lgkmcnt(2)
	s_setprio 1
	v_mfma_f32_32x32x16_bf16 v[48:63], v[66:69], v[70:73], v[48:63]
	s_setprio 0
	ds_read_b64_tr_b16 v[66:67], v168 offset:31232
	ds_read_b64_tr_b16 v[68:69], v168 offset:32384
	v_mov_b32_e32 v86, v82
	v_mov_b32_e32 v87, v84
	v_mov_b32_e32 v84, v83
	v_pk_add_f32 v[82:83], v[86:87], v[84:85]
	v_pk_add_f32 v[124:125], v[148:149], v[116:117]
	v_pk_add_f32 v[126:127], v[146:147], v[104:105]
	s_waitcnt lgkmcnt(2)
	s_setprio 1
	v_mfma_f32_32x32x16_bf16 v[32:47], v[74:77], v[70:73], v[32:47]
	s_setprio 0
	v_cvt_pk_bf16_f32 v70, v128, v129
	v_cvt_pk_bf16_f32 v71, v130, v131
	v_cvt_pk_bf16_f32 v72, v138, v139
	v_cvt_pk_bf16_f32 v73, v142, v143
	ds_read_b64_tr_b16 v[76:77], v168 offset:32448
	ds_read_b64_tr_b16 v[74:75], v168 offset:31296
	v_pk_add_f32 v[102:103], v[152:153], v[122:123]
	v_pk_add_f32 v[118:119], v[150:151], v[120:121]
	s_waitcnt lgkmcnt(2)
	s_setprio 1
	v_mfma_f32_32x32x16_bf16 v[48:63], v[66:69], v[70:73], v[48:63]
	s_setprio 0
	v_mov_b32_e32 v66, v78
	v_mov_b32_e32 v67, v80
	v_mov_b32_e32 v80, v79
	v_add_f32_e64 v78, v66, v80
	v_add_f32_e64 v79, v67, v81
	ds_read_b64_tr_b16 v[66:67], v168 offset:33536
	ds_read_b64_tr_b16 v[68:69], v168 offset:34688
	v_lshlrev_b32_e32 v112, 1, v165
	s_waitcnt lgkmcnt(2)
	s_setprio 1
	v_mfma_f32_32x32x16_bf16 v[32:47], v[74:77], v[70:73], v[32:47]
	s_setprio 0
	v_add_f32_e64 v70, v82, v78
	v_add_f32_e64 v71, v83, v79
	v_cvt_pk_bf16_f32 v74, v104, v105
	v_cvt_pk_bf16_f32 v75, v116, v117
	v_cvt_pk_bf16_f32 v76, v120, v121
	v_cvt_pk_bf16_f32 v77, v122, v123
	ds_read_b64_tr_b16 v[80:81], v168 offset:34752
	ds_read_b64_tr_b16 v[78:79], v168 offset:33600
	s_waitcnt lgkmcnt(0)
	s_setprio 1
	v_mfma_f32_32x32x16_bf16 v[48:63], v[66:69], v[74:77], v[48:63]
	s_setprio 0
	v_add_f32_e64 v66, v70, v71
	v_add_f32_e64 v67, v71, v70
	v_pk_mov_b32 v[68:69], v[126:127], v[124:125] op_sel:[1,0]
	v_mov_b32_e32 v127, v125
	v_pk_add_f32 v[68:69], v[68:69], v[126:127]
	s_barrier
	v_pk_add_f32 v[68:69], v[68:69], v[68:69] op_sel:[0,1] op_sel_hi:[1,0]
	s_setprio 1
	v_mfma_f32_32x32x16_bf16 v[16:31], v[106:109], v[98:101], v[16:31]
	s_setprio 0
	v_max_f32_e32 v65, v0, v16
	v_max_f32_e32 v67, v1, v17
	v_add_f32_e32 v72, v102, v103
	v_max3_f32 v65, v65, v2, v18
	v_max3_f32 v67, v67, v3, v19
	v_add_f32_e32 v70, v118, v119
	v_max3_f32 v65, v65, v4, v20
	v_max3_f32 v67, v67, v5, v21
	s_setprio 1
	v_mfma_f32_32x32x16_bf16 v[32:47], v[78:81], v[74:77], v[32:47]
	s_setprio 0
	v_max3_f32 v65, v65, v6, v22
	v_max3_f32 v67, v67, v7, v23
	s_nop 0
	v_max3_f32 v65, v65, v8, v24
	v_max3_f32 v67, v67, v9, v25
	s_nop 0
	v_max3_f32 v65, v65, v10, v26
	v_max3_f32 v67, v67, v11, v27
	s_nop 0
	v_max3_f32 v65, v65, v12, v28
	v_max3_f32 v67, v67, v13, v29
	s_nop 0
	v_max3_f32 v65, v65, v14, v30
	v_max3_f32 v67, v67, v15, v31
	s_nop 0
	v_max_f32_e32 v65, v65, v67
	ds_bpermute_b32 v67, v167, v65
	s_waitcnt lgkmcnt(0)
	v_max_f32_e32 v65, v65, v67
	s_nop 0
	v_max_f32_e32 v65, v111, v65
	s_nop 0
	v_sub_f32_e32 v67, v111, v65
	v_exp_f32_e32 v74, v67
	v_sub_f32_e32 v7, v7, v65
	v_sub_f32_e32 v6, v6, v65
	v_sub_f32_e32 v5, v5, v65
	v_sub_f32_e32 v4, v4, v65
	v_sub_f32_e32 v3, v3, v65
	v_sub_f32_e32 v2, v2, v65
	v_sub_f32_e32 v1, v1, v65
	v_sub_f32_e32 v0, v0, v65
	v_sub_f32_e32 v19, v19, v65
	v_sub_f32_e32 v18, v18, v65
	v_sub_f32_e32 v17, v17, v65
	v_sub_f32_e32 v16, v16, v65
	v_sub_f32_e32 v69, v21, v65
	v_sub_f32_e32 v71, v20, v65
	v_exp_f32_e32 v90, v0
	v_exp_f32_e32 v92, v16
	v_exp_f32_e32 v91, v1
	v_exp_f32_e32 v93, v17
	v_exp_f32_e32 v20, v2
	v_exp_f32_e32 v94, v18
	v_exp_f32_e32 v21, v3
	v_exp_f32_e32 v95, v19
	v_exp_f32_e32 v96, v4
	v_exp_f32_e32 v97, v5
	v_exp_f32_e32 v100, v6
	v_exp_f32_e32 v101, v7
	ds_read_b64_tr_b16 v[16:17], v168 offset:35840
	ds_read_b64_tr_b16 v[18:19], v168 offset:36992
	v_sub_f32_e32 v31, v31, v65
	v_sub_f32_e32 v30, v30, v65
	v_exp_f32_e32 v78, v30
	v_exp_f32_e32 v79, v31
	v_pk_mul_f32 v[0:1], v[48:49], v[74:75] op_sel_hi:[1,0]
	v_pk_mul_f32 v[30:31], v[46:47], v[74:75] op_sel_hi:[1,0]
	ds_read_b64_tr_b16 v[48:49], v168 offset:37056
	ds_read_b64_tr_b16 v[46:47], v168 offset:35904
	v_sub_f32_e32 v15, v15, v65
	v_sub_f32_e32 v14, v14, v65
	v_sub_f32_e32 v13, v13, v65
	v_sub_f32_e32 v12, v12, v65
	v_sub_f32_e32 v11, v11, v65
	v_sub_f32_e32 v10, v10, v65
	v_sub_f32_e32 v9, v9, v65
	v_sub_f32_e32 v8, v8, v65
	v_sub_f32_e32 v29, v29, v65
	v_sub_f32_e32 v28, v28, v65
	v_sub_f32_e32 v27, v27, v65
	v_sub_f32_e32 v26, v26, v65
	v_exp_f32_e32 v104, v8
	v_exp_f32_e32 v105, v9
	v_exp_f32_e32 v106, v10
	v_exp_f32_e32 v86, v26
	v_exp_f32_e32 v107, v11
	v_exp_f32_e32 v87, v27
	v_exp_f32_e32 v108, v12
	v_exp_f32_e32 v88, v28
	v_exp_f32_e32 v109, v13
	v_exp_f32_e32 v89, v29
	v_exp_f32_e32 v116, v14
	v_exp_f32_e32 v117, v15
	v_pk_mul_f32 v[14:15], v[62:63], v[74:75] op_sel_hi:[1,0]
	v_pk_mul_f32 v[12:13], v[60:61], v[74:75] op_sel_hi:[1,0]
	v_pk_mul_f32 v[10:11], v[58:59], v[74:75] op_sel_hi:[1,0]
	v_pk_mul_f32 v[8:9], v[56:57], v[74:75] op_sel_hi:[1,0]
	v_pk_mul_f32 v[6:7], v[54:55], v[74:75] op_sel_hi:[1,0]
	v_pk_mul_f32 v[4:5], v[52:53], v[74:75] op_sel_hi:[1,0]
	v_pk_mul_f32 v[2:3], v[50:51], v[74:75] op_sel_hi:[1,0]
	v_pk_mul_f32 v[28:29], v[44:45], v[74:75] op_sel_hi:[1,0]
	v_pk_mul_f32 v[26:27], v[42:43], v[74:75] op_sel_hi:[1,0]
	v_cvt_pk_bf16_f32 v42, v90, v91
	v_cvt_pk_bf16_f32 v43, v20, v21
	v_cvt_pk_bf16_f32 v44, v96, v97
	v_cvt_pk_bf16_f32 v45, v100, v101
	v_sub_f32_e32 v25, v25, v65
	v_sub_f32_e32 v24, v24, v65
	v_sub_f32_e32 v23, v23, v65
	v_sub_f32_e32 v22, v22, v65
	s_waitcnt lgkmcnt(2)
	s_setprio 1
	v_mfma_f32_32x32x16_bf16 v[0:15], v[16:19], v[42:45], v[0:15]
	s_setprio 0
	v_exp_f32_e32 v102, v22
	v_exp_f32_e32 v103, v23
	v_exp_f32_e32 v82, v24
	v_exp_f32_e32 v83, v25
	v_pk_add_f32 v[120:121], v[20:21], v[94:95]
	v_pk_mul_f32 v[24:25], v[40:41], v[74:75] op_sel_hi:[1,0]
	v_pk_mul_f32 v[22:23], v[38:39], v[74:75] op_sel_hi:[1,0]
	v_pk_mul_f32 v[20:21], v[36:37], v[74:75] op_sel_hi:[1,0]
	v_pk_mul_f32 v[18:19], v[34:35], v[74:75] op_sel_hi:[1,0]
	v_pk_mul_f32 v[16:17], v[32:33], v[74:75] op_sel_hi:[1,0]
	ds_read_b64_tr_b16 v[32:33], v168 offset:38144
	ds_read_b64_tr_b16 v[34:35], v168 offset:39296
	s_waitcnt lgkmcnt(2)
	s_setprio 1
	v_mfma_f32_32x32x16_bf16 v[16:31], v[46:49], v[42:45], v[16:31]
	s_setprio 0
	ds_read_b64_tr_b16 v[42:43], v168 offset:39360
	ds_read_b64_tr_b16 v[40:41], v168 offset:38208
	v_exp_f32_e32 v98, v71
	v_exp_f32_e32 v99, v69
	v_cvt_pk_bf16_f32 v36, v104, v105
	v_cvt_pk_bf16_f32 v37, v106, v107
	v_cvt_pk_bf16_f32 v38, v108, v109
	v_cvt_pk_bf16_f32 v39, v116, v117
	v_pk_add_f32 v[46:47], v[96:97], v[98:99]
	v_pk_add_f32 v[44:45], v[100:101], v[102:103]
	s_waitcnt lgkmcnt(2)
	s_setprio 1
	v_mfma_f32_32x32x16_bf16 v[0:15], v[32:35], v[36:39], v[0:15]
	s_setprio 0
	v_add_f32_e64 v32, v90, v92
	v_add_f32_e64 v33, v91, v93
	v_mov_b32_e32 v49, v46
	v_mov_b32_e32 v48, v32
	v_mov_b32_e32 v46, v33
	ds_read_b64_tr_b16 v[32:33], v168 offset:40448
	ds_read_b64_tr_b16 v[34:35], v168 offset:41600
	v_pk_add_f32 v[80:81], v[106:107], v[86:87]
	v_pk_add_f32 v[84:85], v[104:105], v[82:83]
	s_waitcnt lgkmcnt(2)
	s_setprio 1
	v_mfma_f32_32x32x16_bf16 v[16:31], v[40:43], v[36:39], v[16:31]
	s_setprio 0
	ds_read_b64_tr_b16 v[42:43], v168 offset:41664
	ds_read_b64_tr_b16 v[40:41], v168 offset:40512
	v_cvt_pk_bf16_f32 v36, v92, v93
	v_cvt_pk_bf16_f32 v37, v94, v95
	v_cvt_pk_bf16_f32 v38, v98, v99
	v_cvt_pk_bf16_f32 v39, v102, v103
	v_pk_add_f32 v[46:47], v[48:49], v[46:47]
	v_mov_b32_e32 v71, v84
	s_waitcnt lgkmcnt(2)
	s_setprio 1
	v_mfma_f32_32x32x16_bf16 v[0:15], v[32:35], v[36:39], v[0:15]
	s_setprio 0
	v_mov_b32_e32 v32, v120
	v_mov_b32_e32 v33, v44
	v_mov_b32_e32 v44, v121
	v_add_f32_e64 v32, v32, v44
	v_add_f32_e64 v33, v33, v45
	v_mov_b32_e32 v73, v85
	v_mov_b32_e32 v69, v80
	v_mov_b32_e32 v67, v81
	v_pk_add_f32 v[32:33], v[46:47], v[32:33]
	s_waitcnt lgkmcnt(0)
	s_setprio 1
	v_mfma_f32_32x32x16_bf16 v[16:31], v[40:43], v[36:39], v[16:31]
	s_setprio 0
	v_add_f32_e64 v40, v70, v72
	v_add_f32_e64 v41, v71, v73
	v_add_f32_e64 v42, v68, v66
	v_add_f32_e64 v43, v69, v67
	v_add_f32_e64 v44, v32, v32
	v_add_f32_e64 v45, v32, v33
	ds_read_b64_tr_b16 v[36:37], v168 offset:42752
	ds_read_b64_tr_b16 v[38:39], v168 offset:43904
	v_pk_add_f32 v[46:47], v[40:41], v[42:43]
	ds_bpermute_b32 v44, v167, v46
	v_pk_add_f32 v[76:77], v[108:109], v[88:89]
	v_pk_add_f32 v[118:119], v[116:117], v[78:79]
	v_cvt_pk_bf16_f32 v32, v82, v83
	v_cvt_pk_bf16_f32 v33, v86, v87
	v_cvt_pk_bf16_f32 v34, v88, v89
	v_cvt_pk_bf16_f32 v35, v78, v79
	v_mov_b32_e32 v111, v76
	v_mov_b32_e32 v115, v77
	v_add_f32_e32 v65, v118, v119
	s_waitcnt lgkmcnt(1)
	s_setprio 1
	v_mfma_f32_32x32x16_bf16 v[0:15], v[36:39], v[32:35], v[0:15]
	s_setprio 0
	v_add_f32_e64 v38, v110, v114
	v_add_f32_e64 v39, v111, v115
	s_waitcnt lgkmcnt(0)
	v_add_f32_e64 v36, v46, v44
	v_add_f32_e64 v37, v47, v45
	v_pk_mul_f32 v[44:45], v[38:39], v[64:65]
	v_pk_add_f32 v[38:39], v[38:39], v[64:65]
	ds_read_b64_tr_b16 v[42:43], v168 offset:43968
	ds_read_b64_tr_b16 v[40:41], v168 offset:42816
	v_mov_b32_e32 v45, v39
	v_pk_add_f32 v[36:37], v[44:45], v[36:37]
	ds_bpermute_b32 v38, v167, v37
	s_waitcnt lgkmcnt(1)
	s_setprio 1
	v_mfma_f32_32x32x16_bf16 v[16:31], v[40:43], v[32:35], v[16:31]
	s_setprio 0
	s_waitcnt lgkmcnt(0)
	s_barrier
	v_add_f32_e32 v32, v37, v38
	v_fmac_f32_e32 v32, v36, v74
	v_div_scale_f32 v33, s[2:3], v32, v32, 1.0
	v_rcp_f32_e32 v34, v33
	s_nop 0
	v_fma_f32 v35, -v33, v34, 1.0
	v_fmac_f32_e32 v34, v35, v34
	v_div_scale_f32 v35, vcc, 1.0, v32, 1.0
	v_mul_f32_e32 v36, v35, v34
	v_fma_f32 v37, -v33, v36, v35
	v_fmac_f32_e32 v36, v37, v34
	v_fma_f32 v33, -v33, v36, v35
	v_div_fmas_f32 v33, v33, v34, v36
	v_div_fixup_f32 v32, v33, v32, 1.0
	v_pk_mul_f32 v[0:1], v[0:1], v[32:33] op_sel_hi:[1,0]
	v_pk_mul_f32 v[2:3], v[2:3], v[32:33] op_sel_hi:[1,0]
	v_mad_i64_i32 v[34:35], s[2:3], v164, s33, v[144:145]
	v_cvt_pk_bf16_f32 v0, v0, v1
	v_cvt_pk_bf16_f32 v1, v2, v3
	v_pk_mul_f32 v[2:3], v[16:17], v[32:33] op_sel_hi:[1,0]
	v_pk_mul_f32 v[16:17], v[18:19], v[32:33] op_sel_hi:[1,0]
	v_lshl_add_u64 v[48:49], v[34:35], 0, v[112:113]
	v_cvt_pk_bf16_f32 v2, v2, v3
	v_cvt_pk_bf16_f32 v3, v16, v17
	global_store_dwordx2 v[48:49], v[0:1], off
	global_store_dwordx2 v[48:49], v[2:3], off offset:64
	v_pk_mul_f32 v[0:1], v[4:5], v[32:33] op_sel_hi:[1,0]
	v_pk_mul_f32 v[2:3], v[6:7], v[32:33] op_sel_hi:[1,0]
	v_cvt_pk_bf16_f32 v0, v0, v1
	v_cvt_pk_bf16_f32 v1, v2, v3
	v_pk_mul_f32 v[2:3], v[20:21], v[32:33] op_sel_hi:[1,0]
	v_pk_mul_f32 v[4:5], v[22:23], v[32:33] op_sel_hi:[1,0]
	v_cvt_pk_bf16_f32 v2, v2, v3
	v_cvt_pk_bf16_f32 v3, v4, v5
	global_store_dwordx2 v[48:49], v[0:1], off offset:16
	global_store_dwordx2 v[48:49], v[2:3], off offset:80
	v_pk_mul_f32 v[0:1], v[8:9], v[32:33] op_sel_hi:[1,0]
	v_pk_mul_f32 v[2:3], v[10:11], v[32:33] op_sel_hi:[1,0]
	v_cvt_pk_bf16_f32 v0, v0, v1
	v_cvt_pk_bf16_f32 v1, v2, v3
	v_pk_mul_f32 v[2:3], v[24:25], v[32:33] op_sel_hi:[1,0]
	v_pk_mul_f32 v[4:5], v[26:27], v[32:33] op_sel_hi:[1,0]
	v_cvt_pk_bf16_f32 v2, v2, v3
	v_cvt_pk_bf16_f32 v3, v4, v5
	global_store_dwordx2 v[48:49], v[0:1], off offset:32
	global_store_dwordx2 v[48:49], v[2:3], off offset:96
	v_pk_mul_f32 v[0:1], v[12:13], v[32:33] op_sel_hi:[1,0]
	v_pk_mul_f32 v[6:7], v[30:31], v[32:33] op_sel_hi:[1,0]
	v_cvt_pk_bf16_f32 v2, v0, v1
	v_pk_mul_f32 v[0:1], v[14:15], v[32:33] op_sel_hi:[1,0]
	s_nop 0
	v_cvt_pk_bf16_f32 v3, v0, v1
	v_pk_mul_f32 v[0:1], v[28:29], v[32:33] op_sel_hi:[1,0]
	s_nop 0
	v_cvt_pk_bf16_f32 v4, v0, v1

.LBB0_1186:
	s_or_b64 exec, exec, s[2:3]
	v_lshlrev_b64 v[2:3], 6, v[24:25]
	v_lshlrev_b32_e32 v4, 3, v32
	v_lshl_add_u64 v[2:3], v[2:3], 1, v[12:13]
	v_lshlrev_b32_e32 v4, 1, v4
	v_mov_b32_e32 v5, v113
	v_lshl_add_u64 v[2:3], v[2:3], 0, v[4:5]
	v_add_co_u32_e32 v2, vcc, 0x2000, v2
	v_and_b32_e32 v6, 31, v29
	s_nop 0
	v_addc_co_u32_e32 v3, vcc, 0, v3, vcc
	global_load_dwordx4 v[204:207], v[2:3], off
	v_mul_u32_u24_e32 v2, 0xd0, v6
	v_add3_u32 v180, 0, v2, v22
	s_waitcnt lgkmcnt(0)
	s_barrier
	ds_read_b128 v[2:5], v180
	ds_read_b128 v[12:15], v180 offset:32
	v_xor_b32_e32 v32, 0x80000000, v28
	v_mov_b32_e32 v33, v32
	v_mov_b32_e32 v34, v32
	v_mov_b32_e32 v35, v32
	v_mov_b32_e32 v36, v32
	v_mov_b32_e32 v37, v32
	v_mov_b32_e32 v38, v32
	v_mov_b32_e32 v39, v32
	v_mov_b32_e32 v40, v32
	v_mov_b32_e32 v41, v32
	v_mov_b32_e32 v42, v32
	v_mov_b32_e32 v43, v32
	v_mov_b32_e32 v44, v32
	v_mov_b32_e32 v45, v32
	v_mov_b32_e32 v46, v32
	v_mov_b32_e32 v47, v32
	v_lshl_add_u64 v[0:1], v[0:1], 0, v[10:11]
	v_lshl_add_u64 v[0:1], v[18:19], 1, v[0:1]
	s_waitcnt lgkmcnt(0)
	s_setprio 1
	v_mfma_f32_32x32x16_bf16 v[64:79], v[2:5], v[100:103], v[32:47]
	s_setprio 0
	ds_read_b128 v[2:5], v180 offset:6656
	ds_read_b128 v[24:27], v180 offset:6688
	v_lshl_add_u64 v[142:143], s[12:13], 0, v[0:1]
	v_mad_i64_i32 v[0:1], s[2:3], v23, s22, v[10:11]
	v_lshlrev_b32_e32 v177, 2, v30
	v_lshrrev_b32_e32 v6, 2, v29
	v_lshl_add_u64 v[0:1], v[16:17], 1, v[0:1]
	s_waitcnt lgkmcnt(0)
	s_setprio 1
	v_mfma_f32_32x32x16_bf16 v[48:63], v[2:5], v[100:103], v[32:47]
	s_setprio 0
	v_and_or_b32 v6, v6, 3, v177
	v_lshlrev_b32_e32 v7, 1, v29
	v_lshl_add_u64 v[162:163], s[12:13], 0, v[0:1]
	v_lshl_add_u64 v[0:1], v[8:9], 0, v[20:21]
	v_mad_u32_u24 v6, v6, s20, 0
	v_and_b32_e32 v7, 32, v7
	v_lshl_add_u64 v[0:1], v[0:1], 0, v[112:113]
	s_setprio 1
	v_mfma_f32_32x32x16_bf16 v[64:79], v[12:15], v[104:107], v[64:79]
	s_setprio 0
	ds_read_b128 v[2:5], v180 offset:64
	ds_read_b128 v[12:15], v180 offset:96
	v_mov_b32_e32 v114, 0
	v_and_b32_e32 v178, 63, v29
	s_mov_b32 s34, 0
	v_add_u32_e32 v173, -3, v166
	v_lshl_add_u64 v[164:165], s[14:15], 0, v[0:1]
	s_mov_b64 s[2:3], 0
	s_setprio 1
	v_mfma_f32_32x32x16_bf16 v[48:63], v[24:27], v[104:107], v[48:63]
	s_setprio 0
	v_mov_b32_e32 v0, 0
	v_mov_b32_e32 v1, v114
	v_mov_b32_e32 v8, v114
	v_mov_b32_e32 v9, v114
	v_mov_b32_e32 v10, v114
	v_mov_b32_e32 v11, v114
	v_mov_b32_e32 v16, 0
	s_waitcnt lgkmcnt(0)
	s_setprio 1
	v_mfma_f32_32x32x16_bf16 v[64:79], v[2:5], v[108:111], v[64:79]
	s_setprio 0
	ds_read_b128 v[2:5], v180 offset:6720
	ds_read_b128 v[24:27], v180 offset:6752
	v_mov_b32_e32 v17, v114
	v_mov_b32_e32 v18, v114
	v_mov_b32_e32 v19, v114
	v_mov_b32_e32 v20, v114
	v_mov_b32_e32 v21, v114
	v_mov_b32_e32 v22, v114
	s_waitcnt lgkmcnt(0)
	s_setprio 1
	v_mfma_f32_32x32x16_bf16 v[48:63], v[2:5], v[108:111], v[48:63]
	s_setprio 0
	ds_read_b128 v[2:5], v180 offset:128
	ds_read_b128 v[80:83], v180 offset:160
	ds_read_b128 v[84:87], v180 offset:6784
	ds_read_b128 v[88:91], v180 offset:6816
	v_mov_b32_e32 v23, v114
	v_mov_b32_e32 v28, v114
	v_mov_b32_e32 v30, v114
	v_mov_b32_e32 v31, v114
	s_waitcnt lgkmcnt(0)
	s_barrier
	s_setprio 1
	v_mfma_f32_32x32x16_bf16 v[64:79], v[12:15], v[116:119], v[64:79]
	s_setprio 0
	v_lshlrev_b32_e32 v12, 3, v29
	v_and_b32_e32 v12, 24, v12
	v_add3_u32 v179, v6, v7, v12
	v_mov_b32_e32 v6, v114
	v_mov_b32_e32 v7, v114
	v_mov_b32_e32 v12, v114
	v_mov_b32_e32 v13, v114
	s_setprio 1
	v_mfma_f32_32x32x16_bf16 v[48:63], v[24:27], v[116:119], v[48:63]
	s_setprio 0
	v_mov_b32_e32 v14, v114
	v_mov_b32_e32 v15, v114
	v_mov_b32_e32 v24, v114
	v_mov_b32_e32 v25, v114
	v_mov_b32_e32 v26, v114
	v_mov_b32_e32 v27, v114
	v_mov_b32_e32 v29, v114
	s_setprio 1
	v_mfma_f32_32x32x16_bf16 v[64:79], v[2:5], v[120:123], v[64:79]
	s_setprio 0
	v_mov_b32_e32 v2, v114
	v_mov_b32_e32 v3, v114
	v_mov_b32_e32 v4, v114
	v_mov_b32_e32 v5, v114
	s_setprio 1
	v_mfma_f32_32x32x16_bf16 v[48:63], v[84:87], v[120:123], v[48:63]
	v_mfma_f32_32x32x16_bf16 v[64:79], v[80:83], v[96:99], v[64:79]
	v_mfma_f32_32x32x16_bf16 v[48:63], v[88:91], v[96:99], v[48:63]
	s_setprio 0
	s_branch .LBB0_1188
.LBB0_1187:
	s_or_b64 exec, exec, s[36:37]
	s_add_i32 s34, s34, 1
	s_bitcmp1_b32 s34, 0
	s_cselect_b32 s36, 0x3400, 0
	v_add_u32_e32 v112, s36, v180
	ds_read_b128 v[132:135], v112
	ds_read_b128 v[136:139], v112 offset:32
	v_exp_f32_e32 v174, v48
	v_exp_f32_e32 v175, v49
	v_exp_f32_e32 v182, v50
	s_waitcnt lgkmcnt(0)
	s_setprio 1
	v_mfma_f32_32x32x16_bf16 v[80:95], v[132:135], v[100:103], v[32:47]
	s_setprio 0
	v_exp_f32_e32 v183, v51
	v_exp_f32_e32 v184, v52
	v_exp_f32_e32 v185, v53
	v_exp_f32_e32 v186, v54
	v_exp_f32_e32 v187, v55
	v_exp_f32_e32 v188, v56
	v_exp_f32_e32 v189, v57
	s_setprio 1
	v_mfma_f32_32x32x16_bf16 v[80:95], v[136:139], v[104:107], v[80:95]
	s_setprio 0
	ds_read_b128 v[132:135], v112 offset:64
	ds_read_b128 v[136:139], v112 offset:96
	v_exp_f32_e32 v190, v58
	v_exp_f32_e32 v191, v59
	v_exp_f32_e32 v192, v60
	v_exp_f32_e32 v193, v61
	v_exp_f32_e32 v194, v62
	v_exp_f32_e32 v195, v63
	s_waitcnt lgkmcnt(0)
	s_setprio 1
	v_mfma_f32_32x32x16_bf16 v[80:95], v[132:135], v[108:111], v[80:95]
	s_setprio 0
	ds_read_b128 v[132:135], v112 offset:128
	ds_read_b128 v[48:51], v112 offset:160
	s_and_b64 s[18:19], s[18:19], exec
	s_cselect_b32 s18, 0x2400, 0
	v_exp_f32_e32 v198, v64
	v_exp_f32_e32 v199, v65
	v_exp_f32_e32 v200, v70
	s_setprio 1
	v_mfma_f32_32x32x16_bf16 v[80:95], v[136:139], v[116:119], v[80:95]
	s_setprio 0
	v_exp_f32_e32 v201, v71
	v_exp_f32_e32 v202, v72
	v_exp_f32_e32 v203, v73
	v_exp_f32_e32 v76, v76
	v_cvt_pk_bf16_f32 v71, v200, v201
	v_exp_f32_e32 v78, v78
	v_exp_f32_e32 v79, v79
	s_waitcnt lgkmcnt(0)
	s_setprio 1
	v_mfma_f32_32x32x16_bf16 v[80:95], v[132:135], v[120:123], v[80:95]
	s_setprio 0
	ds_read_b128 v[132:135], v112 offset:6656
	ds_read_b128 v[146:149], v112 offset:6688
	v_exp_f32_e32 v77, v77
	v_cmp_eq_u32_e32 vcc, s34, v173
	v_lshl_add_u64 v[142:143], v[142:143], 0, s[24:25]
	v_lshl_add_u64 v[162:163], v[162:163], 0, s[24:25]
	s_or_b64 s[2:3], vcc, s[2:3]
	s_setprio 1
	v_mfma_f32_32x32x16_bf16 v[80:95], v[48:51], v[96:99], v[80:95]
	s_waitcnt lgkmcnt(0)
	v_mfma_f32_32x32x16_bf16 v[48:63], v[132:135], v[100:103], v[32:47]
	s_setprio 0
	ds_read_b128 v[150:153], v112 offset:6720
	ds_read_b128 v[154:157], v112 offset:6752
	ds_read_b128 v[158:161], v112 offset:6784
	ds_read_b128 v[136:139], v112 offset:6816
	v_add_u32_e32 v112, s18, v179
	v_lshl_add_u64 v[164:165], v[164:165], 0, s[0:1]
	s_setprio 1
	v_mfma_f32_32x32x16_bf16 v[48:63], v[146:149], v[104:107], v[48:63]
	s_setprio 0
	v_exp_f32_e32 v146, v66
	v_exp_f32_e32 v147, v67
	v_exp_f32_e32 v148, v68
	v_exp_f32_e32 v149, v69
	ds_read_b64_tr_b16 v[64:65], v112 offset:26624
	ds_read_b64_tr_b16 v[66:67], v112 offset:27776
	v_cvt_pk_bf16_f32 v68, v198, v199
	v_cvt_pk_bf16_f32 v69, v146, v147
	s_waitcnt lgkmcnt(0)
	s_setprio 1
	v_mfma_f32_32x32x16_bf16 v[48:63], v[150:153], v[108:111], v[48:63]
	s_setprio 0
	v_exp_f32_e32 v150, v74
	v_exp_f32_e32 v151, v75
	ds_read_b64_tr_b16 v[74:75], v112 offset:27840
	ds_read_b64_tr_b16 v[72:73], v112 offset:26688
	v_cvt_pk_bf16_f32 v70, v148, v149
	v_pk_add_f32 v[146:147], v[182:183], v[146:147]
	v_pk_add_f32 v[198:199], v[174:175], v[198:199]
	v_pk_add_f32 v[148:149], v[184:185], v[148:149]
	s_setprio 1
	v_mfma_f32_32x32x16_bf16 v[0:15], v[64:67], v[68:71], v[0:15]
	s_setprio 0
	ds_read_b64_tr_b16 v[64:65], v112 offset:28928
	ds_read_b64_tr_b16 v[66:67], v112 offset:30080
	v_add_f32_e64 v152, v194, v78
	v_add_f32_e64 v153, v195, v79
	s_waitcnt lgkmcnt(0)
	s_setprio 1
	v_mfma_f32_32x32x16_bf16 v[16:31], v[72:75], v[68:71], v[16:31]
	s_setprio 0
	ds_read_b64_tr_b16 v[74:75], v112 offset:30144
	ds_read_b64_tr_b16 v[72:73], v112 offset:28992
	v_cvt_pk_bf16_f32 v68, v202, v203
	v_cvt_pk_bf16_f32 v69, v150, v151
	v_cvt_pk_bf16_f32 v70, v76, v77
	v_cvt_pk_bf16_f32 v71, v78, v79
	s_setprio 1
	v_mfma_f32_32x32x16_bf16 v[48:63], v[154:157], v[116:119], v[48:63]
	s_setprio 0
	v_add_f32_e64 v154, v192, v76
	v_add_f32_e64 v155, v193, v77
	v_add_f32_e64 v156, v190, v150
	v_add_f32_e64 v157, v191, v151
	s_setprio 1
	v_mfma_f32_32x32x16_bf16 v[0:15], v[64:67], v[68:71], v[0:15]
	s_waitcnt lgkmcnt(0)
	v_mfma_f32_32x32x16_bf16 v[16:31], v[72:75], v[68:71], v[16:31]
	s_setprio 0
	v_cvt_pk_bf16_f32 v68, v174, v175
	v_cvt_pk_bf16_f32 v69, v182, v183
	v_cvt_pk_bf16_f32 v70, v184, v185
	v_cvt_pk_bf16_f32 v71, v186, v187
	s_setprio 1
	v_mfma_f32_32x32x16_bf16 v[48:63], v[158:161], v[120:123], v[48:63]
	s_setprio 0
	v_add_f32_e64 v160, v186, v200
	v_add_f32_e64 v161, v187, v201
	v_pk_mov_b32 v[200:201], v[198:199], v[146:147] op_sel:[1,0]
	v_mov_b32_e32 v199, v147
	v_pk_add_f32 v[64:65], v[200:201], v[198:199]
	v_pk_mov_b32 v[78:79], v[148:149], v[160:161] op_sel:[1,0]
	v_pk_add_f32 v[76:77], v[64:65], v[64:65] op_sel_hi:[0,1]
	ds_read_b64_tr_b16 v[64:65], v112 offset:31232
	ds_read_b64_tr_b16 v[66:67], v112 offset:32384
	ds_read_b64_tr_b16 v[74:75], v112 offset:32448
	ds_read_b64_tr_b16 v[72:73], v112 offset:31296
	s_waitcnt lgkmcnt(0)
	s_setprio 1
	v_mfma_f32_32x32x16_bf16 v[0:15], v[64:67], v[68:71], v[0:15]
	s_setprio 0
	ds_read_b64_tr_b16 v[64:65], v112 offset:33536
	ds_read_b64_tr_b16 v[66:67], v112 offset:34688
	v_mov_b32_e32 v149, v161
	v_add_f32_e64 v78, v78, v148
	v_add_f32_e64 v79, v79, v149
	v_pk_add_f32 v[158:159], v[188:189], v[202:203]
	v_pk_add_f32 v[78:79], v[78:79], v[78:79] op_sel_hi:[0,1]
	v_add_f32_e32 v147, v158, v159
	v_add_f32_e32 v149, v156, v157
	s_setprio 1
	v_mfma_f32_32x32x16_bf16 v[16:31], v[72:75], v[68:71], v[16:31]
	s_setprio 0
	ds_read_b64_tr_b16 v[74:75], v112 offset:34752
	ds_read_b64_tr_b16 v[72:73], v112 offset:33600
	v_cvt_pk_bf16_f32 v68, v188, v189
	v_cvt_pk_bf16_f32 v69, v190, v191
	v_cvt_pk_bf16_f32 v70, v192, v193
	v_cvt_pk_bf16_f32 v71, v194, v195
	v_mov_b32_e32 v146, v154
	v_mov_b32_e32 v148, v155
	s_waitcnt lgkmcnt(0)
	s_setprio 1
	v_mfma_f32_32x32x16_bf16 v[0:15], v[64:67], v[68:71], v[0:15]
	s_setprio 0
	v_mov_b32_e32 v76, v152
	v_mov_b32_e32 v78, v153
	v_add_f32_e64 v146, v146, v148
	v_add_f32_e64 v147, v147, v149
	v_add_f32_e64 v64, v76, v78
	v_add_f32_e64 v65, v77, v79
	v_pk_add_f32 v[64:65], v[146:147], v[64:65]
	s_barrier
	s_setprio 1
	v_mfma_f32_32x32x16_bf16 v[16:31], v[72:75], v[68:71], v[16:31]
	s_setprio 0
	v_add_f32_e32 v64, v64, v65
	v_add_f32_e32 v114, v114, v64
	v_mov_b64_e32 v[64:65], v[80:81]
	v_mov_b64_e32 v[66:67], v[82:83]
	v_mov_b64_e32 v[68:69], v[84:85]
	v_mov_b64_e32 v[70:71], v[86:87]
	v_mov_b64_e32 v[72:73], v[88:89]
	s_setprio 1
	v_mfma_f32_32x32x16_bf16 v[48:63], v[136:139], v[96:99], v[48:63]
	s_setprio 0
	v_mov_b64_e32 v[74:75], v[90:91]
	v_mov_b64_e32 v[76:77], v[92:93]
	v_mov_b64_e32 v[78:79], v[94:95]
	s_andn2_b64 exec, exec, s[2:3]
	s_cbranch_execz .LBB0_1192

.LBB0_1225:
	s_waitcnt lgkmcnt(0)
	s_barrier
	ds_read_b128 v[0:3], v118 offset:9216
	v_add_u32_e32 v92, v103, v104
	ds_read_b128 v[4:7], v92
	v_add_u32_e32 v93, v105, v104
	v_mov_b32_e32 v121, 0
	s_waitcnt lgkmcnt(0)
	s_setprio 1
	v_mfma_f32_32x32x16_bf16 v[32:47], v[0:3], v[4:7], 0
	ds_read_b128 v[0:3], v118 offset:13824
	s_waitcnt lgkmcnt(0)
	v_mfma_f32_32x32x16_bf16 v[16:31], v[0:3], v[4:7], 0
	s_setprio 0
	ds_read_b128 v[0:3], v93 offset:46080
	ds_read_b128 v[122:125], v118 offset:9248
	ds_read_b128 v[126:129], v92 offset:32
	s_waitcnt lgkmcnt(0)
	s_setprio 1
	v_mfma_f32_32x32x16_bf16 v[32:47], v[122:125], v[126:129], v[32:47]
	ds_read_b128 v[122:125], v118 offset:13856
	s_waitcnt lgkmcnt(0)
	v_mfma_f32_32x32x16_bf16 v[16:31], v[122:125], v[126:129], v[16:31]
	ds_read_b128 v[122:125], v93 offset:46112
	v_mfma_f32_32x32x16_bf16 v[0:15], v[0:3], v[4:7], 0
	s_waitcnt lgkmcnt(0)
	v_mfma_f32_32x32x16_bf16 v[0:15], v[122:125], v[126:129], v[0:15]
	ds_read_b128 v[122:125], v118 offset:9280
	ds_read_b128 v[126:129], v92 offset:64
	s_waitcnt lgkmcnt(0)
	v_mfma_f32_32x32x16_bf16 v[32:47], v[122:125], v[126:129], v[32:47]
	ds_read_b128 v[122:125], v118 offset:13888
	s_waitcnt lgkmcnt(0)
	v_mfma_f32_32x32x16_bf16 v[16:31], v[122:125], v[126:129], v[16:31]
	ds_read_b128 v[122:125], v93 offset:46144
	s_waitcnt lgkmcnt(0)
	v_mfma_f32_32x32x16_bf16 v[0:15], v[122:125], v[126:129], v[0:15]
	ds_read_b128 v[122:125], v118 offset:9312
	ds_read_b128 v[126:129], v92 offset:96
	s_waitcnt lgkmcnt(0)
	v_mfma_f32_32x32x16_bf16 v[32:47], v[122:125], v[126:129], v[32:47]
	s_setprio 0
	ds_read_b128 v[122:125], v118 offset:13920
	ds_read_b128 v[130:133], v93 offset:46176
	ds_read2st64_b32 v[92:93], v120 offset0:253 offset1:255
	s_waitcnt lgkmcnt(0)
	s_setprio 1
	v_mfma_f32_32x32x16_bf16 v[16:31], v[122:125], v[126:129], v[16:31]
	v_mov_b32_e32 v122, 0
	v_mfma_f32_32x32x16_bf16 v[0:15], v[130:133], v[126:129], v[0:15]
	s_setprio 0
	s_mov_b64 s[16:17], exec
	v_readlane_b32 s38, v255, 46
	v_readlane_b32 s39, v255, 47
	s_and_b64 s[38:39], s[16:17], s[38:39]
	s_mov_b64 exec, s[38:39]
	s_cbranch_execz .LBB0_1227
	ds_read_b32 v122, v110 offset:64512
	s_waitcnt lgkmcnt(0)
	v_sub_f32_e32 v122, v122, v92
	v_mul_f32_e32 v122, 0x3fb8aa3b, v122
	v_exp_f32_e32 v122, v122
	s_nop 0
	v_mul_f32_e32 v122, v32, v122

.LBB0_1287:
	s_or_b64 exec, exec, s[16:17]
	v_add_f32_e32 v31, v122, v32
	v_add_f32_e32 v31, 0, v31
	v_add_f32_e32 v47, v121, v16
	v_add_f32_e32 v31, v31, v47
	v_add_f32_e32 v47, v33, v17
	v_add_f32_e32 v31, v31, v47
	v_add_f32_e32 v47, v34, v18
	v_add_f32_e32 v31, v31, v47
	v_add_f32_e32 v47, v35, v19
	v_add_f32_e32 v31, v31, v47
	v_add_f32_e32 v47, v36, v20
	v_add_f32_e32 v31, v31, v47
	v_add_f32_e32 v47, v37, v21
	v_add_f32_e32 v31, v31, v47
	v_add_f32_e32 v47, v38, v22
	v_add_f32_e32 v31, v31, v47
	v_add_f32_e32 v47, v39, v23
	v_add_f32_e32 v31, v31, v47
	v_add_f32_e32 v47, v40, v24
	v_add_f32_e32 v31, v31, v47
	v_add_f32_e32 v47, v41, v25
	v_add_f32_e32 v31, v31, v47
	v_add_f32_e32 v47, v42, v26
	v_add_f32_e32 v31, v31, v47
	v_add_f32_e32 v47, v43, v27
	v_add_f32_e32 v31, v31, v47
	v_add_f32_e32 v47, v44, v28
	v_add_f32_e32 v31, v31, v47
	v_add_f32_e32 v47, v45, v29
	v_add_f32_e32 v31, v31, v47
	v_add_u32_e32 v47, 0x6800, v119
	ds_read2_b64 v[124:127], v47 offset0:128 offset1:130
	v_mul_f32_e32 v0, v0, v93
	v_mul_f32_e32 v1, v1, v93
	v_mul_f32_e32 v2, v2, v93
	v_mul_f32_e32 v3, v3, v93
	v_mul_f32_e32 v4, v4, v93
	v_mul_f32_e32 v5, v5, v93
	v_mul_f32_e32 v6, v6, v93
	v_mul_f32_e32 v7, v7, v93
	v_mul_f32_e32 v8, v8, v93
	v_mul_f32_e32 v9, v9, v93
	v_mul_f32_e32 v10, v10, v93
	v_mul_f32_e32 v11, v11, v93
	v_mul_f32_e32 v12, v12, v93
	v_mul_f32_e32 v13, v13, v93
	v_mul_f32_e32 v14, v14, v93
	v_mul_f32_e32 v15, v15, v93
	v_cvt_pk_bf16_f32 v128, v122, v121
	v_cvt_pk_bf16_f32 v129, v33, v34
	v_cvt_pk_bf16_f32 v130, v35, v36
	v_cvt_pk_bf16_f32 v131, v37, v38
	ds_read2_b64 v[34:37], v47 offset0:132 offset1:134
	v_cvt_pk_bf16_f32 v38, v39, v40
	s_waitcnt lgkmcnt(0)
	s_setprio 1
	v_mfma_f32_32x32x16_bf16 v[0:15], v[124:127], v[128:131], v[0:15]
	s_setprio 0
	v_cvt_pk_bf16_f32 v39, v41, v42
	v_cvt_pk_bf16_f32 v40, v43, v44
	v_cvt_pk_bf16_f32 v41, v45, v46
	ds_read2_b64 v[42:45], v47 offset0:136 offset1:138
	v_add_f32_e32 v33, v46, v30
	v_add_f32_e32 v31, v31, v33
	v_cvt_pk_bf16_f32 v16, v32, v16
	s_setprio 1
	v_mfma_f32_32x32x16_bf16 v[0:15], v[34:37], v[38:41], v[0:15]
	s_setprio 0
	v_cvt_pk_bf16_f32 v17, v17, v18
	v_cvt_pk_bf16_f32 v18, v19, v20
	v_cvt_pk_bf16_f32 v19, v21, v22
	ds_read2_b64 v[32:35], v47 offset0:140 offset1:142
	v_cvt_pk_bf16_f32 v20, v23, v24
	v_cvt_pk_bf16_f32 v21, v25, v26
	v_cvt_pk_bf16_f32 v22, v27, v28
	s_waitcnt lgkmcnt(0)
	s_setprio 1
	v_mfma_f32_32x32x16_bf16 v[0:15], v[42:45], v[16:19], v[0:15]
	s_setprio 0
	v_cvt_pk_bf16_f32 v23, v29, v30
	s_mul_hi_i32 s3, s49, 0x78787879
	s_lshr_b32 s16, s3, 31
	s_ashr_i32 s3, s3, 5
	s_add_i32 s3, s3, s16
	s_mul_i32 s16, s3, 0xffffffbc
	ds_bpermute_b32 v17, v106, v31
	s_setprio 1
	v_mfma_f32_32x32x16_bf16 v[0:15], v[32:35], v[20:23], v[0:15]
	s_setprio 0
	ds_read_b32 v18, v107
	ds_read_b32 v19, v120 offset:65024
	s_add_i32 s38, s49, s16
	s_and_b32 s39, s3, 1
	s_ashr_i32 s34, s3, 3
	s_cmp_eq_u32 s39, 0
	s_cselect_b64 s[16:17], -1, 0
	s_cmp_eq_u32 s39, 1
	s_cselect_b64 vcc, -1, 0
	s_cmp_gt_i32 s38, 3
	s_mov_b64 s[38:39], -1
	s_cbranch_scc0 .LBB0_1293
	s_andn2_b64 vcc, exec, vcc
	s_cbranch_vccnz .LBB0_1290
	s_mul_i32 s38, s3, 0x1100
	s_add_i32 s38, s38, s48
	v_add_u32_e32 v16, s38, v114
	s_mov_b64 s[38:39], 0
